# BAR steps 3/5/7 (modes 0/2): first two V fragments of the P.V block prefetched into v[240:247] at the start of the previous W block; ladder regenerated
# speedup vs baseline: 1.0056x; 1.0004x over previous
.LBB0_641:
	s_add_i32 s24, s23, -7
	s_lshl_b32 s92, s24, 13
	s_add_u32 vcc_lo, s100, s92
	s_addc_u32 vcc_hi, s101, 0
	global_load_dwordx4 v[52:55], v248, vcc
	s_add_i32 s24, s23, -8
	s_lshl_b32 s92, s24, 7
	s_add_u32 vcc_lo, s98, s92
	s_addc_u32 vcc_hi, s99, 0
	global_load_dwordx4 v[56:59], v249, vcc
	s_mul_i32 s26, s25, 0x2400
	s_add_i32 s24, s23, -7
	s_add_i32 s27, s26, 0xffffdc00
	s_cmp_lg_u32 s25, 0
	s_cselect_b32 s27, s27, 0x9000
	v_add_u32_e32 v1, s27, v163
	ds_read_b128 v[60:63], v1 offset:36864
	ds_read_b128 v[114:117], v1 offset:36896
	ds_read_b128 v[118:121], v1 offset:41472
	ds_read_b128 v[134:137], v1 offset:41504
	ds_read_b128 v[146:149], v1 offset:36928
	ds_read_b128 v[150:153], v1 offset:36960
	ds_read_b128 v[196:199], v1 offset:41536
	ds_read_b128 v[200:203], v1 offset:41568
	s_setprio 3
	v_cvt_pk_bf16_f32 v204, v102, v103
	v_cvt_pk_bf16_f32 v205, v104, v105
	v_cvt_pk_bf16_f32 v206, v98, v99
	v_cvt_pk_bf16_f32 v207, v100, v101
	s_waitcnt lgkmcnt(7)
	s_nop 0
	v_mfma_f32_32x32x16_bf16 v[18:33], v[60:63], v[204:207], v[18:33]
	v_add_f32_e32 v1, v102, v103
	v_add_f32_e32 v1, v1, v104
	v_add_f32_e32 v1, v1, v105
	s_waitcnt lgkmcnt(5)
	v_mfma_f32_32x32x16_bf16 v[2:17], v[118:121], v[204:207], v[2:17]
	v_cvt_pk_bf16_f32 v60, v194, v187
	v_cvt_pk_bf16_f32 v61, v186, v185
	v_cvt_pk_bf16_f32 v62, v133, v132
	v_cvt_pk_bf16_f32 v63, v131, v130
	v_add_f32_e32 v1, v1, v98
	v_add_f32_e32 v1, v1, v99
	v_add_f32_e32 v1, v1, v100
	v_add_f32_e32 v1, v1, v101
	s_nop 0
	v_mfma_f32_32x32x16_bf16 v[18:33], v[114:117], v[60:63], v[18:33]
	v_add_f32_e32 v1, v1, v194
	v_add_f32_e32 v1, v1, v187
	v_add_f32_e32 v1, v1, v186
	v_add_f32_e32 v1, v1, v185
	s_waitcnt lgkmcnt(4)
	v_mfma_f32_32x32x16_bf16 v[2:17], v[134:137], v[60:63], v[2:17]
	v_cvt_pk_bf16_f32 v98, v129, v128
	v_cvt_pk_bf16_f32 v99, v127, v126
	v_cvt_pk_bf16_f32 v100, v125, v124
	v_cvt_pk_bf16_f32 v101, v123, v122
	v_add_f32_e32 v1, v1, v133
	v_add_f32_e32 v1, v1, v132
	v_add_f32_e32 v1, v1, v131
	v_add_f32_e32 v1, v1, v130
	s_waitcnt lgkmcnt(3)
	v_mfma_f32_32x32x16_bf16 v[18:33], v[146:149], v[98:101], v[18:33]
	v_add_f32_e32 v1, v1, v129
	v_add_f32_e32 v1, v1, v128
	v_add_f32_e32 v1, v1, v127
	v_add_f32_e32 v1, v1, v126
	s_waitcnt lgkmcnt(1)
	v_mfma_f32_32x32x16_bf16 v[2:17], v[196:199], v[98:101], v[2:17]
	v_cvt_pk_bf16_f32 v60, v109, v108
	v_cvt_pk_bf16_f32 v61, v107, v106
	v_cvt_pk_bf16_f32 v62, v113, v112
	v_cvt_pk_bf16_f32 v63, v111, v110
	v_add_f32_e32 v1, v1, v125
	v_add_f32_e32 v1, v1, v124
	v_add_f32_e32 v1, v1, v123
	v_add_f32_e32 v1, v1, v122
	s_nop 0
	v_mfma_f32_32x32x16_bf16 v[18:33], v[150:153], v[60:63], v[18:33]
	v_add_f32_e32 v1, v1, v109
	v_add_f32_e32 v1, v1, v108
	v_add_f32_e32 v1, v1, v107
	v_add_f32_e32 v1, v1, v106
	s_waitcnt lgkmcnt(0)
	v_mfma_f32_32x32x16_bf16 v[2:17], v[200:203], v[60:63], v[2:17]
	v_add_f32_e32 v1, v1, v113
	v_add_f32_e32 v1, v1, v112
	v_add_f32_e32 v1, v1, v111
	v_add_f32_e32 v1, v1, v110
	s_setprio 2
	s_waitcnt lgkmcnt(0)
	s_barrier
	ds_read_b128 v[240:243], v165 offset:18432
	ds_read_b128 v[244:247], v165 offset:23040
	ds_read_b128 v[130:133], v165 offset:18464
	ds_read_b128 v[146:149], v165 offset:23072
	v_exp_f32_e32 v185, v82
	v_exp_f32_e32 v186, v83
	v_exp_f32_e32 v187, v84
	v_exp_f32_e32 v194, v85
	v_exp_f32_e32 v195, v86
	v_exp_f32_e32 v196, v87
	v_exp_f32_e32 v197, v88
	v_exp_f32_e32 v198, v89
	s_waitcnt lgkmcnt(2)
	v_mfma_f32_32x32x16_bf16 v[114:129], v[240:243], v[158:161], v[34:49]
	s_waitcnt lgkmcnt(1)
	v_mfma_f32_32x32x16_bf16 v[98:113], v[244:247], v[158:161], v[34:49]
	v_exp_f32_e32 v199, v90
	v_exp_f32_e32 v200, v91
	v_exp_f32_e32 v201, v92
	v_exp_f32_e32 v202, v93
	v_exp_f32_e32 v134, v94
	v_exp_f32_e32 v135, v95
	v_exp_f32_e32 v136, v96
	v_exp_f32_e32 v137, v97
	v_mfma_f32_32x32x16_bf16 v[114:129], v[130:133], v[154:157], v[114:129]
	v_exp_f32_e32 v96, v66
	v_exp_f32_e32 v97, v67
	v_exp_f32_e32 v203, v68
	v_exp_f32_e32 v204, v69
	v_exp_f32_e32 v130, v70
	v_exp_f32_e32 v131, v71
	v_exp_f32_e32 v132, v72
	v_exp_f32_e32 v133, v73
	s_waitcnt lgkmcnt(0)
	v_mfma_f32_32x32x16_bf16 v[98:113], v[146:149], v[154:157], v[98:113]
	v_exp_f32_e32 v205, v74
	v_exp_f32_e32 v206, v75
	v_exp_f32_e32 v207, v76
	v_exp_f32_e32 v208, v77
	v_exp_f32_e32 v209, v78
	v_exp_f32_e32 v210, v79
	v_exp_f32_e32 v211, v80
	v_exp_f32_e32 v212, v81
	v_add_u32_e32 v88, s26, v163
	ds_read_b128 v[240:243], v165 offset:27648
	ds_read_b128 v[244:247], v165 offset:32256
	ds_read_b128 v[60:63], v88 offset:41472
	ds_read_b128 v[64:67], v88 offset:36864
	ds_read_b128 v[68:71], v88 offset:36896
	ds_read_b128 v[72:75], v88 offset:41504
	ds_read_b128 v[76:79], v88 offset:36928
	ds_read_b128 v[80:83], v88 offset:41536
	ds_read_b128 v[84:87], v88 offset:36960
	ds_read_b128 v[88:91], v88 offset:41568
	s_cmp_gt_i32 s25, 2
	s_cselect_b32 s27, -3, 2
	s_add_i32 s27, s27, s25
	s_add_i32 s26, s23, -6
	s_mulk_i32 s27, 0x2400
	s_min_u32 s26, s26, s13
	v_add_u32_e32 v51, s27, v182
	s_min_u32 s24, s24, s13
	s_lshl_b32 s92, s26, 13
	s_waitcnt vmcnt(3)
	ds_write_b128 v182, v[138:141]
	s_waitcnt vmcnt(2)
	ds_write_b128 v51, v[142:145] offset:36864
	v_add_f32_e32 v1, v50, v1
	s_add_u32 vcc_lo, s100, s92
	s_addc_u32 vcc_hi, s101, 0
	global_load_dwordx4 v[146:149], v248, vcc
	s_lshl_b32 s92, s24, 7
	s_add_u32 vcc_lo, s98, s92
	s_addc_u32 vcc_hi, s99, 0
	global_load_dwordx4 v[150:153], v249, vcc
	s_add_i32 s27, s25, 1
	s_setprio 1
	v_cvt_pk_bf16_f32 v92, v185, v186
	v_cvt_pk_bf16_f32 v93, v187, v194
	v_cvt_pk_bf16_f32 v94, v195, v196
	v_cvt_pk_bf16_f32 v95, v197, v198
	s_waitcnt lgkmcnt(8)
	s_nop 0
	v_mfma_f32_32x32x16_bf16 v[18:33], v[64:67], v[92:95], v[18:33]
	v_add_f32_e32 v213, v185, v186
	v_add_f32_e32 v213, v213, v187
	v_add_f32_e32 v213, v213, v194
	s_nop 0
	v_mfma_f32_32x32x16_bf16 v[2:17], v[60:63], v[92:95], v[2:17]
	v_cvt_pk_bf16_f32 v64, v199, v200
	v_cvt_pk_bf16_f32 v65, v201, v202
	v_cvt_pk_bf16_f32 v66, v134, v135
	v_cvt_pk_bf16_f32 v67, v136, v137
	v_add_f32_e32 v213, v213, v195
	v_add_f32_e32 v213, v213, v196
	v_add_f32_e32 v213, v213, v197
	v_add_f32_e32 v213, v213, v198
	s_waitcnt lgkmcnt(7)
	v_mfma_f32_32x32x16_bf16 v[18:33], v[68:71], v[64:67], v[18:33]
	v_add_f32_e32 v213, v213, v199
	v_add_f32_e32 v213, v213, v200
	v_add_f32_e32 v213, v213, v201
	v_add_f32_e32 v213, v213, v202
	s_waitcnt lgkmcnt(6)
	v_mfma_f32_32x32x16_bf16 v[2:17], v[72:75], v[64:67], v[2:17]
	v_cvt_pk_bf16_f32 v60, v96, v97
	v_cvt_pk_bf16_f32 v61, v203, v204
	v_cvt_pk_bf16_f32 v62, v130, v131
	v_cvt_pk_bf16_f32 v63, v132, v133
	v_add_f32_e32 v213, v213, v134
	v_add_f32_e32 v213, v213, v135
	v_add_f32_e32 v213, v213, v136
	v_add_f32_e32 v213, v213, v137
	s_waitcnt lgkmcnt(5)
	v_mfma_f32_32x32x16_bf16 v[18:33], v[76:79], v[60:63], v[18:33]
	v_add_f32_e32 v213, v213, v96
	v_add_f32_e32 v213, v213, v97
	v_add_f32_e32 v213, v213, v203
	v_add_f32_e32 v213, v213, v204
	s_waitcnt lgkmcnt(4)
	v_mfma_f32_32x32x16_bf16 v[2:17], v[80:83], v[60:63], v[2:17]
	v_cvt_pk_bf16_f32 v64, v205, v206
	v_cvt_pk_bf16_f32 v65, v207, v208
	v_cvt_pk_bf16_f32 v66, v209, v210
	v_cvt_pk_bf16_f32 v67, v211, v212
	v_add_f32_e32 v213, v213, v130
	v_add_f32_e32 v213, v213, v131
	v_add_f32_e32 v213, v213, v132
	v_add_f32_e32 v213, v213, v133
	s_waitcnt lgkmcnt(3)
	v_mfma_f32_32x32x16_bf16 v[18:33], v[84:87], v[64:67], v[18:33]
	v_add_f32_e32 v213, v213, v205
	v_add_f32_e32 v213, v213, v206
	v_add_f32_e32 v213, v213, v207
	v_add_f32_e32 v213, v213, v208
	s_waitcnt lgkmcnt(2)
	v_mfma_f32_32x32x16_bf16 v[2:17], v[88:91], v[64:67], v[2:17]
	v_add_f32_e32 v213, v213, v209
	v_add_f32_e32 v213, v213, v210
	v_add_f32_e32 v213, v213, v211
	v_add_f32_e32 v213, v213, v212
	s_setprio 0
	ds_read_b128 v[64:67], v165 offset:27680
	ds_read_b128 v[72:75], v165 offset:32288
	s_cmp_lg_u32 s25, 4
	s_cselect_b32 s24, s27, 0
	s_waitcnt lgkmcnt(2)
	v_mfma_f32_32x32x16_bf16 v[130:145], v[240:243], v[158:161], v[34:49]
	v_exp_f32_e32 v185, v114
	v_exp_f32_e32 v186, v115
	v_exp_f32_e32 v187, v116
	v_exp_f32_e32 v194, v117
	v_exp_f32_e32 v195, v118
	v_exp_f32_e32 v196, v119
	v_exp_f32_e32 v197, v120
	v_exp_f32_e32 v198, v121
	s_waitcnt lgkmcnt(1)
	v_mfma_f32_32x32x16_bf16 v[82:97], v[244:247], v[158:161], v[34:49]
	v_exp_f32_e32 v199, v122
	v_exp_f32_e32 v200, v123
	v_exp_f32_e32 v201, v124
	v_exp_f32_e32 v202, v125
	v_exp_f32_e32 v122, v126
	v_exp_f32_e32 v123, v127
	v_exp_f32_e32 v124, v128
	v_exp_f32_e32 v125, v129
	v_mfma_f32_32x32x16_bf16 v[130:145], v[64:67], v[154:157], v[130:145]
	v_exp_f32_e32 v126, v98
	v_exp_f32_e32 v127, v99
	v_exp_f32_e32 v128, v100
	v_exp_f32_e32 v129, v101
	v_exp_f32_e32 v203, v102
	v_exp_f32_e32 v204, v103
	v_exp_f32_e32 v205, v104
	v_exp_f32_e32 v206, v105
	s_waitcnt lgkmcnt(0)
	v_mfma_f32_32x32x16_bf16 v[82:97], v[72:75], v[154:157], v[82:97]
	v_exp_f32_e32 v102, v106
	v_exp_f32_e32 v103, v107
	v_exp_f32_e32 v104, v108
	v_exp_f32_e32 v105, v109
	v_exp_f32_e32 v106, v110
	v_exp_f32_e32 v107, v111
	v_exp_f32_e32 v108, v112
	v_exp_f32_e32 v109, v113
	s_mul_i32 vcc_lo, s24, 0x2400
	v_add_u32_e32 v251, vcc_lo, v163
	ds_read_b128 v[240:243], v251 offset:36864
	ds_read_b128 v[244:247], v251 offset:41472
	s_cmp_gt_i32 s24, 2
	s_cselect_b32 s25, -3, 2
	s_add_i32 s25, s25, s24
	s_mulk_i32 s25, 0x2400
	v_add_u32_e32 v50, s25, v182
	s_add_i32 s25, s24, 1
	s_cmp_lg_u32 s24, 4
	s_cselect_b32 s24, s25, 0
	s_add_i32 s25, s23, -5
	s_min_u32 s25, s25, s13
	s_lshl_b32 s92, s25, 13
	s_waitcnt vmcnt(3)
	ds_write_b128 v182, v[52:55] offset:9216
	s_waitcnt vmcnt(2)
	ds_write_b128 v50, v[56:59] offset:36864
	s_add_u32 vcc_lo, s100, s92
	s_addc_u32 vcc_hi, s101, 0
	global_load_dwordx4 v[118:121], v248, vcc
	s_lshl_b32 s92, s26, 7
	s_add_u32 vcc_lo, s98, s92
	s_addc_u32 vcc_hi, s99, 0
	global_load_dwordx4 v[114:117], v249, vcc
	s_mul_i32 s26, s24, 0x2400
	s_add_i32 s27, s26, 0xffffdc00
	s_cmp_lg_u32 s24, 0
	s_cselect_b32 s27, s27, 0x9000
	v_add_u32_e32 v78, s27, v163
	ds_read_b128 v[54:57], v78 offset:36896
	ds_read_b128 v[62:65], v78 offset:41504
	ds_read_b128 v[66:69], v78 offset:36928
	ds_read_b128 v[70:73], v78 offset:36960
	ds_read_b128 v[74:77], v78 offset:41536
	ds_read_b128 v[78:81], v78 offset:41568
	s_setprio 3
	v_cvt_pk_bf16_f32 v98, v185, v186
	v_cvt_pk_bf16_f32 v99, v187, v194
	v_cvt_pk_bf16_f32 v100, v195, v196
	v_cvt_pk_bf16_f32 v101, v197, v198
	s_waitcnt lgkmcnt(6)
	s_nop 0
	v_mfma_f32_32x32x16_bf16 v[18:33], v[240:243], v[98:101], v[18:33]
	v_add_f32_e32 v110, v185, v186
	v_add_f32_e32 v110, v110, v187
	v_add_f32_e32 v110, v110, v194
	v_mfma_f32_32x32x16_bf16 v[2:17], v[244:247], v[98:101], v[2:17]
	v_cvt_pk_bf16_f32 v50, v199, v200
	v_cvt_pk_bf16_f32 v51, v201, v202
	v_cvt_pk_bf16_f32 v52, v122, v123
	v_cvt_pk_bf16_f32 v53, v124, v125
	v_add_f32_e32 v110, v110, v195
	v_add_f32_e32 v110, v110, v196
	v_add_f32_e32 v110, v110, v197
	v_add_f32_e32 v110, v110, v198
	s_nop 0
	s_waitcnt lgkmcnt(5)
	v_mfma_f32_32x32x16_bf16 v[18:33], v[54:57], v[50:53], v[18:33]
	v_add_f32_e32 v110, v110, v199
	v_add_f32_e32 v110, v110, v200
	v_add_f32_e32 v110, v110, v201
	v_add_f32_e32 v110, v110, v202
	s_waitcnt lgkmcnt(4)
	v_mfma_f32_32x32x16_bf16 v[2:17], v[62:65], v[50:53], v[2:17]
	v_cvt_pk_bf16_f32 v54, v126, v127
	v_cvt_pk_bf16_f32 v55, v128, v129
	v_cvt_pk_bf16_f32 v56, v203, v204
	v_cvt_pk_bf16_f32 v57, v205, v206
	v_add_f32_e32 v110, v110, v122
	v_add_f32_e32 v110, v110, v123
	v_add_f32_e32 v110, v110, v124
	v_add_f32_e32 v110, v110, v125
	s_waitcnt lgkmcnt(3)
	v_mfma_f32_32x32x16_bf16 v[18:33], v[66:69], v[54:57], v[18:33]
	v_add_f32_e32 v110, v110, v126
	v_add_f32_e32 v110, v110, v127
	v_add_f32_e32 v110, v110, v128
	v_add_f32_e32 v110, v110, v129
	s_waitcnt lgkmcnt(1)
	v_mfma_f32_32x32x16_bf16 v[2:17], v[74:77], v[54:57], v[2:17]
	v_cvt_pk_bf16_f32 v50, v102, v103
	v_cvt_pk_bf16_f32 v51, v104, v105
	v_cvt_pk_bf16_f32 v52, v106, v107
	v_cvt_pk_bf16_f32 v53, v108, v109
	v_add_f32_e32 v110, v110, v203
	v_add_f32_e32 v110, v110, v204
	v_add_f32_e32 v110, v110, v205
	v_add_f32_e32 v110, v110, v206
	s_nop 0
	v_mfma_f32_32x32x16_bf16 v[18:33], v[70:73], v[50:53], v[18:33]
	v_add_f32_e32 v110, v110, v102
	v_add_f32_e32 v110, v110, v103
	v_add_f32_e32 v110, v110, v104
	v_add_f32_e32 v110, v110, v105
	s_waitcnt lgkmcnt(0)
	v_mfma_f32_32x32x16_bf16 v[2:17], v[78:81], v[50:53], v[2:17]
	v_add_f32_e32 v110, v110, v106
	v_add_f32_e32 v110, v110, v107
	v_add_f32_e32 v110, v110, v108
	v_add_f32_e32 v110, v110, v109
	s_setprio 2
	s_waitcnt lgkmcnt(0)
	s_barrier
	ds_read_b128 v[240:243], v165
	ds_read_b128 v[244:247], v165 offset:4608
	ds_read_b128 v[102:105], v165 offset:32
	ds_read_b128 v[106:109], v165 offset:4640
	v_add_f32_e32 v1, v1, v213
	v_exp_f32_e32 v185, v130
	v_exp_f32_e32 v186, v131
	v_exp_f32_e32 v187, v132
	v_exp_f32_e32 v194, v133
	v_exp_f32_e32 v195, v134
	v_exp_f32_e32 v196, v135
	v_exp_f32_e32 v197, v136
	v_exp_f32_e32 v198, v137
	s_waitcnt lgkmcnt(2)
	v_mfma_f32_32x32x16_bf16 v[66:81], v[240:243], v[158:161], v[34:49]
	v_mfma_f32_32x32x16_bf16 v[50:65], v[244:247], v[158:161], v[34:49]
	v_exp_f32_e32 v134, v138
	v_exp_f32_e32 v135, v139
	v_exp_f32_e32 v136, v140
	v_exp_f32_e32 v137, v141
	v_exp_f32_e32 v138, v142
	v_exp_f32_e32 v139, v143
	v_exp_f32_e32 v140, v144
	v_exp_f32_e32 v141, v145
	s_waitcnt lgkmcnt(1)
	v_mfma_f32_32x32x16_bf16 v[66:81], v[102:105], v[154:157], v[66:81]
	v_exp_f32_e32 v142, v82
	v_exp_f32_e32 v143, v83
	v_exp_f32_e32 v144, v84
	v_exp_f32_e32 v145, v85
	v_exp_f32_e32 v199, v86
	v_exp_f32_e32 v200, v87
	v_exp_f32_e32 v201, v88
	v_exp_f32_e32 v202, v89
	s_waitcnt lgkmcnt(0)
	v_mfma_f32_32x32x16_bf16 v[50:65], v[106:109], v[154:157], v[50:65]
	v_exp_f32_e32 v203, v90
	v_exp_f32_e32 v204, v91
	v_exp_f32_e32 v205, v92
	v_exp_f32_e32 v206, v93
	v_exp_f32_e32 v207, v94
	v_exp_f32_e32 v208, v95
	v_exp_f32_e32 v209, v96
	v_exp_f32_e32 v210, v97
	v_add_f32_e32 v1, v1, v110
	v_add_u32_e32 v111, s26, v163
	ds_read_b128 v[240:243], v165 offset:9216
	ds_read_b128 v[244:247], v165 offset:13824
	ds_read_b128 v[82:85], v111 offset:41472
	ds_read_b128 v[86:89], v111 offset:36864
	ds_read_b128 v[90:93], v111 offset:36896
	ds_read_b128 v[94:97], v111 offset:41504
	ds_read_b128 v[98:101], v111 offset:36928
	ds_read_b128 v[102:105], v111 offset:41536
	ds_read_b128 v[106:109], v111 offset:36960
	ds_read_b128 v[110:113], v111 offset:41568
	s_cmp_gt_i32 s24, 2
	s_cselect_b32 s27, -3, 2
	s_add_i32 s27, s27, s24
	s_mulk_i32 s27, 0x2400
	v_add_u32_e32 v250, s27, v182
	s_mov_b32 s27, 0x18950000
	s_waitcnt vmcnt(3)
	ds_write_b128 v182, v[146:149] offset:18432
	s_waitcnt vmcnt(2)
	ds_write_b128 v250, v[150:153] offset:36864
	s_add_i32 s92, s23, -4
	s_lshl_b32 s92, s92, 13
	s_add_u32 vcc_lo, s100, s92
	s_addc_u32 vcc_hi, s101, 0
	global_load_dwordx4 v[126:129], v248, vcc
	s_lshl_b32 s92, s25, 7
	s_add_u32 vcc_lo, s98, s92
	s_addc_u32 vcc_hi, s99, 0
	global_load_dwordx4 v[122:125], v249, vcc
	s_add_i32 s26, s24, 1
	s_setprio 1
	v_cvt_pk_bf16_f32 v130, v185, v186
	v_cvt_pk_bf16_f32 v131, v187, v194
	v_cvt_pk_bf16_f32 v132, v195, v196
	v_cvt_pk_bf16_f32 v133, v197, v198
	s_waitcnt lgkmcnt(8)
	s_nop 0
	v_mfma_f32_32x32x16_bf16 v[18:33], v[86:89], v[130:133], v[18:33]
	v_add_f32_e32 v146, v185, v186
	v_add_f32_e32 v146, v146, v187
	v_add_f32_e32 v146, v146, v194
	s_nop 0
	v_mfma_f32_32x32x16_bf16 v[2:17], v[82:85], v[130:133], v[2:17]
	v_cvt_pk_bf16_f32 v86, v134, v135
	v_cvt_pk_bf16_f32 v87, v136, v137
	v_cvt_pk_bf16_f32 v88, v138, v139
	v_cvt_pk_bf16_f32 v89, v140, v141
	v_add_f32_e32 v146, v146, v195
	v_add_f32_e32 v146, v146, v196
	v_add_f32_e32 v146, v146, v197
	v_add_f32_e32 v146, v146, v198
	s_waitcnt lgkmcnt(7)
	v_mfma_f32_32x32x16_bf16 v[18:33], v[90:93], v[86:89], v[18:33]
	v_add_f32_e32 v146, v146, v134
	v_add_f32_e32 v146, v146, v135
	v_add_f32_e32 v146, v146, v136
	v_add_f32_e32 v146, v146, v137
	s_waitcnt lgkmcnt(6)
	v_mfma_f32_32x32x16_bf16 v[2:17], v[94:97], v[86:89], v[2:17]
	v_cvt_pk_bf16_f32 v82, v142, v143
	v_cvt_pk_bf16_f32 v83, v144, v145
	v_cvt_pk_bf16_f32 v84, v199, v200
	v_cvt_pk_bf16_f32 v85, v201, v202
	v_add_f32_e32 v146, v146, v138
	v_add_f32_e32 v146, v146, v139
	v_add_f32_e32 v146, v146, v140
	v_add_f32_e32 v146, v146, v141
	s_waitcnt lgkmcnt(5)
	v_mfma_f32_32x32x16_bf16 v[18:33], v[98:101], v[82:85], v[18:33]
	v_add_f32_e32 v146, v146, v142
	v_add_f32_e32 v146, v146, v143
	v_add_f32_e32 v146, v146, v144
	v_add_f32_e32 v146, v146, v145
	s_waitcnt lgkmcnt(4)
	v_mfma_f32_32x32x16_bf16 v[2:17], v[102:105], v[82:85], v[2:17]
	v_cvt_pk_bf16_f32 v86, v203, v204
	v_cvt_pk_bf16_f32 v87, v205, v206
	v_cvt_pk_bf16_f32 v88, v207, v208
	v_cvt_pk_bf16_f32 v89, v209, v210
	v_add_f32_e32 v146, v146, v199
	v_add_f32_e32 v146, v146, v200
	v_add_f32_e32 v146, v146, v201
	v_add_f32_e32 v146, v146, v202
	s_waitcnt lgkmcnt(3)
	v_mfma_f32_32x32x16_bf16 v[18:33], v[106:109], v[86:89], v[18:33]
	v_add_f32_e32 v146, v146, v203
	v_add_f32_e32 v146, v146, v204
	v_add_f32_e32 v146, v146, v205
	v_add_f32_e32 v146, v146, v206
	s_waitcnt lgkmcnt(2)
	v_mfma_f32_32x32x16_bf16 v[2:17], v[110:113], v[86:89], v[2:17]
	v_add_f32_e32 v146, v146, v207
	v_add_f32_e32 v146, v146, v208
	v_add_f32_e32 v146, v146, v209
	v_add_f32_e32 v146, v146, v210
	s_setprio 0
	ds_read_b128 v[130:133], v165 offset:9248
	ds_read_b128 v[138:141], v165 offset:13856
	s_cmp_lg_u32 s24, 4
	s_cselect_b32 s24, s26, 0
	s_waitcnt lgkmcnt(2)
	v_mfma_f32_32x32x16_bf16 v[98:113], v[240:243], v[158:161], v[34:49]
	v_exp_f32_e32 v142, v66
	v_exp_f32_e32 v143, v67
	v_exp_f32_e32 v144, v68
	v_exp_f32_e32 v145, v69
	v_exp_f32_e32 v147, v70
	v_exp_f32_e32 v148, v71
	v_exp_f32_e32 v149, v72
	v_exp_f32_e32 v150, v73
	s_waitcnt lgkmcnt(1)
	v_mfma_f32_32x32x16_bf16 v[82:97], v[244:247], v[158:161], v[34:49]
	v_exp_f32_e32 v151, v74
	v_exp_f32_e32 v152, v75
	v_exp_f32_e32 v153, v76
	v_exp_f32_e32 v178, v77
	v_exp_f32_e32 v134, v78
	v_exp_f32_e32 v135, v79
	v_exp_f32_e32 v136, v80
	v_exp_f32_e32 v137, v81
	v_mfma_f32_32x32x16_bf16 v[98:113], v[130:133], v[154:157], v[98:113]
	v_exp_f32_e32 v179, v50
	v_exp_f32_e32 v185, v51
	v_exp_f32_e32 v186, v52
	v_exp_f32_e32 v187, v53
	v_exp_f32_e32 v194, v54
	v_exp_f32_e32 v195, v55
	v_exp_f32_e32 v196, v56
	v_exp_f32_e32 v197, v57
	s_waitcnt lgkmcnt(0)
	v_mfma_f32_32x32x16_bf16 v[82:97], v[138:141], v[154:157], v[82:97]
	v_exp_f32_e32 v198, v58
	v_exp_f32_e32 v199, v59
	v_exp_f32_e32 v200, v60
	v_exp_f32_e32 v201, v61
	v_exp_f32_e32 v138, v62
	v_exp_f32_e32 v139, v63
	v_exp_f32_e32 v140, v64
	v_exp_f32_e32 v141, v65
	s_mul_i32 vcc_lo, s24, 0x2400
	v_add_u32_e32 v251, vcc_lo, v163
	ds_read_b128 v[240:243], v251 offset:36864
	ds_read_b128 v[244:247], v251 offset:41472
	s_cmp_gt_i32 s24, 2
	s_cselect_b32 s25, -3, 2
	s_add_i32 s25, s25, s24
	s_mulk_i32 s25, 0x2400
	v_add_u32_e32 v50, s25, v182
	s_add_i32 s25, s24, 1
	s_cmp_lg_u32 s24, 4
	s_cselect_b32 s25, s25, 0
	s_add_i32 s24, s23, -3
	s_min_u32 s26, s24, s13
	s_lshl_b32 s92, s26, 13
	s_waitcnt vmcnt(3)
	ds_write_b128 v182, v[118:121] offset:27648
	s_waitcnt vmcnt(2)
	ds_write_b128 v50, v[114:117] offset:36864
	s_add_u32 vcc_lo, s100, s92
	s_addc_u32 vcc_hi, s101, 0
	global_load_dwordx4 v[118:121], v248, vcc
	s_add_i32 s92, s23, -4
	s_lshl_b32 s92, s92, 7
	s_add_u32 vcc_lo, s98, s92
	s_addc_u32 vcc_hi, s99, 0
	global_load_dwordx4 v[114:117], v249, vcc
	s_mul_i32 s27, s25, 0x2400
	s_add_i32 s28, s27, 0xffffdc00
	s_cmp_lg_u32 s25, 0
	s_cselect_b32 s28, s28, 0x9000
	v_add_u32_e32 v78, s28, v163
	ds_read_b128 v[54:57], v78 offset:36896
	ds_read_b128 v[62:65], v78 offset:41504
	ds_read_b128 v[66:69], v78 offset:36928
	ds_read_b128 v[70:73], v78 offset:36960
	ds_read_b128 v[74:77], v78 offset:41536
	ds_read_b128 v[78:81], v78 offset:41568
	s_setprio 3
	v_cvt_pk_bf16_f32 v130, v142, v143
	v_cvt_pk_bf16_f32 v131, v144, v145
	v_cvt_pk_bf16_f32 v132, v147, v148
	v_cvt_pk_bf16_f32 v133, v149, v150
	s_waitcnt lgkmcnt(6)
	s_nop 0
	v_mfma_f32_32x32x16_bf16 v[18:33], v[240:243], v[130:133], v[18:33]
	v_add_f32_e32 v176, v142, v143
	v_add_f32_e32 v176, v176, v144
	v_add_f32_e32 v176, v176, v145
	v_mfma_f32_32x32x16_bf16 v[2:17], v[244:247], v[130:133], v[2:17]
	v_cvt_pk_bf16_f32 v50, v151, v152
	v_cvt_pk_bf16_f32 v51, v153, v178
	v_cvt_pk_bf16_f32 v52, v134, v135
	v_cvt_pk_bf16_f32 v53, v136, v137
	v_add_f32_e32 v176, v176, v147
	v_add_f32_e32 v176, v176, v148
	v_add_f32_e32 v176, v176, v149
	v_add_f32_e32 v176, v176, v150
	s_nop 0
	s_waitcnt lgkmcnt(5)
	v_mfma_f32_32x32x16_bf16 v[18:33], v[54:57], v[50:53], v[18:33]
	v_add_f32_e32 v176, v176, v151
	v_add_f32_e32 v176, v176, v152
	v_add_f32_e32 v176, v176, v153
	v_add_f32_e32 v176, v176, v178
	s_waitcnt lgkmcnt(4)
	v_mfma_f32_32x32x16_bf16 v[2:17], v[62:65], v[50:53], v[2:17]
	v_cvt_pk_bf16_f32 v54, v179, v185
	v_cvt_pk_bf16_f32 v55, v186, v187
	v_cvt_pk_bf16_f32 v56, v194, v195
	v_cvt_pk_bf16_f32 v57, v196, v197
	v_add_f32_e32 v176, v176, v134
	v_add_f32_e32 v176, v176, v135
	v_add_f32_e32 v176, v176, v136
	v_add_f32_e32 v176, v176, v137
	s_waitcnt lgkmcnt(3)
	v_mfma_f32_32x32x16_bf16 v[18:33], v[66:69], v[54:57], v[18:33]
	v_add_f32_e32 v176, v176, v179
	v_add_f32_e32 v176, v176, v185
	v_add_f32_e32 v176, v176, v186
	v_add_f32_e32 v176, v176, v187
	s_waitcnt lgkmcnt(1)
	v_mfma_f32_32x32x16_bf16 v[2:17], v[74:77], v[54:57], v[2:17]
	v_cvt_pk_bf16_f32 v50, v198, v199
	v_cvt_pk_bf16_f32 v51, v200, v201
	v_cvt_pk_bf16_f32 v52, v138, v139
	v_cvt_pk_bf16_f32 v53, v140, v141
	v_add_f32_e32 v176, v176, v194
	v_add_f32_e32 v176, v176, v195
	v_add_f32_e32 v176, v176, v196
	v_add_f32_e32 v176, v176, v197
	s_nop 0
	v_mfma_f32_32x32x16_bf16 v[18:33], v[70:73], v[50:53], v[18:33]
	v_add_f32_e32 v176, v176, v198
	v_add_f32_e32 v176, v176, v199
	v_add_f32_e32 v176, v176, v200
	v_add_f32_e32 v176, v176, v201
	s_waitcnt lgkmcnt(0)
	v_mfma_f32_32x32x16_bf16 v[2:17], v[78:81], v[50:53], v[2:17]
	v_add_f32_e32 v176, v176, v138
	v_add_f32_e32 v176, v176, v139
	v_add_f32_e32 v176, v176, v140
	v_add_f32_e32 v176, v176, v141
	s_setprio 2
	s_waitcnt lgkmcnt(0)
	s_barrier
	ds_read_b128 v[240:243], v165 offset:18432
	ds_read_b128 v[244:247], v165 offset:23040
	ds_read_b128 v[134:137], v165 offset:18464
	ds_read_b128 v[138:141], v165 offset:23072
	v_add_f32_e32 v1, v1, v146
	v_exp_f32_e32 v142, v98
	v_exp_f32_e32 v143, v99
	v_exp_f32_e32 v144, v100
	v_exp_f32_e32 v145, v101
	v_exp_f32_e32 v146, v102
	v_exp_f32_e32 v147, v103
	v_exp_f32_e32 v148, v104
	v_exp_f32_e32 v149, v105
	s_waitcnt lgkmcnt(2)
	v_mfma_f32_32x32x16_bf16 v[66:81], v[240:243], v[158:161], v[34:49]
	v_mfma_f32_32x32x16_bf16 v[50:65], v[244:247], v[158:161], v[34:49]
	v_exp_f32_e32 v150, v106
	v_exp_f32_e32 v151, v107
	v_exp_f32_e32 v152, v108
	v_exp_f32_e32 v153, v109
	v_exp_f32_e32 v177, v110
	v_exp_f32_e32 v178, v111
	v_exp_f32_e32 v179, v112
	v_exp_f32_e32 v185, v113
	s_waitcnt lgkmcnt(1)
	v_mfma_f32_32x32x16_bf16 v[66:81], v[134:137], v[154:157], v[66:81]
	v_exp_f32_e32 v186, v82
	v_exp_f32_e32 v187, v83
	v_exp_f32_e32 v194, v84
	v_exp_f32_e32 v195, v85
	v_exp_f32_e32 v134, v86
	v_exp_f32_e32 v135, v87
	v_exp_f32_e32 v136, v88
	v_exp_f32_e32 v137, v89
	s_waitcnt lgkmcnt(0)
	v_mfma_f32_32x32x16_bf16 v[50:65], v[138:141], v[154:157], v[50:65]
	v_exp_f32_e32 v196, v90
	v_exp_f32_e32 v197, v91
	v_exp_f32_e32 v198, v92
	v_exp_f32_e32 v199, v93
	v_exp_f32_e32 v138, v94
	v_exp_f32_e32 v139, v95
	v_exp_f32_e32 v140, v96
	v_exp_f32_e32 v141, v97
	s_cmp_gt_i32 s25, 2
	s_cselect_b32 s28, -3, 2
	s_waitcnt vmcnt(3)
	ds_write_b128 v182, v[126:129]
	s_add_i32 s28, s28, s25
	v_add_u32_e32 v126, s27, v163
	s_add_i32 s27, s23, -2
	s_mulk_i32 s28, 0x2400
	s_min_u32 s27, s27, s13
	v_add_u32_e32 v82, s28, v182
	s_lshl_b32 s92, s27, 13
	s_waitcnt vmcnt(2)
	ds_write_b128 v82, v[122:125] offset:36864
	ds_read_b128 v[240:243], v165 offset:27648
	ds_read_b128 v[244:247], v165 offset:32256
	ds_read_b128 v[82:85], v126 offset:41472
	ds_read_b128 v[86:89], v126 offset:36864
	ds_read_b128 v[90:93], v126 offset:36896
	ds_read_b128 v[94:97], v126 offset:41504
	ds_read_b128 v[106:109], v126 offset:36928
	ds_read_b128 v[110:113], v126 offset:41536
	ds_read_b128 v[122:125], v126 offset:36960
	ds_read_b128 v[126:129], v126 offset:41568
	s_add_u32 vcc_lo, s100, s92
	s_addc_u32 vcc_hi, s101, 0
	global_load_dwordx4 v[98:101], v248, vcc
	s_lshl_b32 s92, s26, 7
	s_add_u32 vcc_lo, s98, s92
	s_addc_u32 vcc_hi, s99, 0
	global_load_dwordx4 v[102:105], v249, vcc
	v_add_f32_e32 v1, v1, v176
	s_add_i32 s28, s25, 1
	s_setprio 1
	v_cvt_pk_bf16_f32 v130, v142, v143
	v_cvt_pk_bf16_f32 v131, v144, v145
	v_cvt_pk_bf16_f32 v132, v146, v147
	v_cvt_pk_bf16_f32 v133, v148, v149
	s_waitcnt lgkmcnt(6)
	s_nop 0
	v_mfma_f32_32x32x16_bf16 v[18:33], v[86:89], v[130:133], v[18:33]
	v_add_f32_e32 v176, v142, v143
	v_add_f32_e32 v176, v176, v144
	v_add_f32_e32 v176, v176, v145
	s_nop 0
	v_mfma_f32_32x32x16_bf16 v[2:17], v[82:85], v[130:133], v[2:17]
	v_cvt_pk_bf16_f32 v86, v150, v151
	v_cvt_pk_bf16_f32 v87, v152, v153
	v_cvt_pk_bf16_f32 v88, v177, v178
	v_cvt_pk_bf16_f32 v89, v179, v185
	v_add_f32_e32 v176, v176, v146
	v_add_f32_e32 v176, v176, v147
	v_add_f32_e32 v176, v176, v148
	v_add_f32_e32 v176, v176, v149
	s_waitcnt lgkmcnt(5)
	v_mfma_f32_32x32x16_bf16 v[18:33], v[90:93], v[86:89], v[18:33]
	v_add_f32_e32 v176, v176, v150
	v_add_f32_e32 v176, v176, v151
	v_add_f32_e32 v176, v176, v152
	v_add_f32_e32 v176, v176, v153
	s_waitcnt lgkmcnt(4)
	v_mfma_f32_32x32x16_bf16 v[2:17], v[94:97], v[86:89], v[2:17]
	v_cvt_pk_bf16_f32 v82, v186, v187
	v_cvt_pk_bf16_f32 v83, v194, v195
	v_cvt_pk_bf16_f32 v84, v134, v135
	v_cvt_pk_bf16_f32 v85, v136, v137
	v_add_f32_e32 v176, v176, v177
	v_add_f32_e32 v176, v176, v178
	v_add_f32_e32 v176, v176, v179
	v_add_f32_e32 v176, v176, v185
	s_waitcnt lgkmcnt(3)
	v_mfma_f32_32x32x16_bf16 v[18:33], v[106:109], v[82:85], v[18:33]
	v_add_f32_e32 v176, v176, v186
	v_add_f32_e32 v176, v176, v187
	v_add_f32_e32 v176, v176, v194
	v_add_f32_e32 v176, v176, v195
	s_waitcnt lgkmcnt(2)
	v_mfma_f32_32x32x16_bf16 v[2:17], v[110:113], v[82:85], v[2:17]
	v_cvt_pk_bf16_f32 v86, v196, v197
	v_cvt_pk_bf16_f32 v87, v198, v199
	v_cvt_pk_bf16_f32 v88, v138, v139
	v_cvt_pk_bf16_f32 v89, v140, v141
	v_add_f32_e32 v176, v176, v134
	v_add_f32_e32 v176, v176, v135
	v_add_f32_e32 v176, v176, v136
	v_add_f32_e32 v176, v176, v137
	s_waitcnt lgkmcnt(1)
	v_mfma_f32_32x32x16_bf16 v[18:33], v[122:125], v[86:89], v[18:33]
	v_add_f32_e32 v176, v176, v196
	v_add_f32_e32 v176, v176, v197
	v_add_f32_e32 v176, v176, v198
	v_add_f32_e32 v176, v176, v199
	s_waitcnt lgkmcnt(0)
	v_mfma_f32_32x32x16_bf16 v[2:17], v[126:129], v[86:89], v[2:17]
	v_add_f32_e32 v176, v176, v138
	v_add_f32_e32 v176, v176, v139
	v_add_f32_e32 v176, v176, v140
	v_add_f32_e32 v176, v176, v141
	s_setprio 0
	ds_read_b128 v[106:109], v165 offset:27680
	ds_read_b128 v[122:125], v165 offset:32288
	s_cmp_lg_u32 s25, 4
	s_cselect_b32 s25, s28, 0
	s_waitcnt lgkmcnt(2)
	v_mfma_f32_32x32x16_bf16 v[138:153], v[240:243], v[158:161], v[34:49]
	v_exp_f32_e32 v126, v66
	v_exp_f32_e32 v127, v67
	v_exp_f32_e32 v128, v68
	v_exp_f32_e32 v129, v69
	v_exp_f32_e32 v130, v70
	v_exp_f32_e32 v131, v71
	v_exp_f32_e32 v132, v72
	v_exp_f32_e32 v133, v73
	s_waitcnt lgkmcnt(1)
	v_mfma_f32_32x32x16_bf16 v[82:97], v[244:247], v[158:161], v[34:49]
	v_exp_f32_e32 v134, v74
	v_exp_f32_e32 v135, v75
	v_exp_f32_e32 v136, v76
	v_exp_f32_e32 v137, v77
	v_exp_f32_e32 v177, v78
	v_exp_f32_e32 v178, v79
	v_exp_f32_e32 v179, v80
	v_exp_f32_e32 v185, v81
	v_mfma_f32_32x32x16_bf16 v[138:153], v[106:109], v[154:157], v[138:153]
	v_exp_f32_e32 v80, v50
	v_exp_f32_e32 v81, v51
	v_exp_f32_e32 v186, v52
	v_exp_f32_e32 v187, v53
	v_exp_f32_e32 v194, v54
	v_exp_f32_e32 v195, v55
	v_exp_f32_e32 v196, v56
	v_exp_f32_e32 v197, v57
	s_waitcnt lgkmcnt(0)
	v_mfma_f32_32x32x16_bf16 v[82:97], v[122:125], v[154:157], v[82:97]
	v_exp_f32_e32 v198, v58
	v_exp_f32_e32 v199, v59
	v_exp_f32_e32 v200, v60
	v_exp_f32_e32 v201, v61
	v_exp_f32_e32 v122, v62
	v_exp_f32_e32 v123, v63
	v_exp_f32_e32 v124, v64
	v_exp_f32_e32 v125, v65
	s_mul_i32 vcc_lo, s25, 0x2400
	v_add_u32_e32 v251, vcc_lo, v163
	ds_read_b128 v[240:243], v251 offset:36864
	ds_read_b128 v[244:247], v251 offset:41472
	s_cmp_gt_i32 s25, 2
	s_cselect_b32 s26, -3, 2
	s_add_i32 s26, s26, s25
	s_mulk_i32 s26, 0x2400
	v_add_u32_e32 v50, s26, v182
	s_add_i32 s26, s25, 1
	s_cmp_lg_u32 s25, 4
	s_cselect_b32 s25, s26, 0
	s_add_i32 s26, s23, -1
	s_min_u32 s26, s26, s13
	s_lshl_b32 s92, s26, 13
	s_waitcnt vmcnt(3)
	ds_write_b128 v182, v[118:121] offset:9216
	s_waitcnt vmcnt(2)
	ds_write_b128 v50, v[114:117] offset:36864
	s_add_u32 vcc_lo, s100, s92
	s_addc_u32 vcc_hi, s101, 0
	global_load_dwordx4 v[56:59], v248, vcc
	s_lshl_b32 s92, s27, 7
	s_add_u32 vcc_lo, s98, s92
	s_addc_u32 vcc_hi, s99, 0
	global_load_dwordx4 v[52:55], v249, vcc
	s_nop 0
	s_mul_i32 s27, s25, 0x2400
	s_add_i32 s28, s27, 0xffffdc00
	s_cmp_lg_u32 s25, 0
	s_cselect_b32 s28, s28, 0x9000
	v_add_u32_e32 v50, s28, v163
	ds_read_b128 v[64:67], v50 offset:36896
	ds_read_b128 v[72:75], v50 offset:41504
	ds_read_b128 v[76:79], v50 offset:36928
	ds_read_b128 v[106:109], v50 offset:36960
	ds_read_b128 v[110:113], v50 offset:41536
	ds_read_b128 v[114:117], v50 offset:41568
	s_setprio 3
	v_cvt_pk_bf16_f32 v118, v126, v127
	v_cvt_pk_bf16_f32 v119, v128, v129
	v_cvt_pk_bf16_f32 v120, v130, v131
	v_cvt_pk_bf16_f32 v121, v132, v133
	s_waitcnt lgkmcnt(6)
	s_nop 0
	v_mfma_f32_32x32x16_bf16 v[18:33], v[240:243], v[118:121], v[18:33]
	v_add_f32_e32 v50, v126, v127
	v_add_f32_e32 v50, v50, v128
	v_add_f32_e32 v50, v50, v129
	v_mfma_f32_32x32x16_bf16 v[2:17], v[244:247], v[118:121], v[2:17]
	v_cvt_pk_bf16_f32 v60, v134, v135
	v_cvt_pk_bf16_f32 v61, v136, v137
	v_cvt_pk_bf16_f32 v62, v177, v178
	v_cvt_pk_bf16_f32 v63, v179, v185
	v_add_f32_e32 v50, v50, v130
	v_add_f32_e32 v50, v50, v131
	v_add_f32_e32 v50, v50, v132
	v_add_f32_e32 v50, v50, v133
	s_nop 0
	s_waitcnt lgkmcnt(5)
	v_mfma_f32_32x32x16_bf16 v[18:33], v[64:67], v[60:63], v[18:33]
	v_add_f32_e32 v50, v50, v134
	v_add_f32_e32 v50, v50, v135
	v_add_f32_e32 v50, v50, v136
	v_add_f32_e32 v50, v50, v137
	s_waitcnt lgkmcnt(4)
	v_mfma_f32_32x32x16_bf16 v[2:17], v[72:75], v[60:63], v[2:17]
	v_cvt_pk_bf16_f32 v64, v80, v81
	v_cvt_pk_bf16_f32 v65, v186, v187
	v_cvt_pk_bf16_f32 v66, v194, v195
	v_cvt_pk_bf16_f32 v67, v196, v197
	v_add_f32_e32 v50, v50, v177
	v_add_f32_e32 v50, v50, v178
	v_add_f32_e32 v50, v50, v179
	v_add_f32_e32 v50, v50, v185
	s_waitcnt lgkmcnt(3)
	v_mfma_f32_32x32x16_bf16 v[18:33], v[76:79], v[64:67], v[18:33]
	v_add_f32_e32 v50, v50, v80
	v_add_f32_e32 v50, v50, v81
	v_add_f32_e32 v50, v50, v186
	v_add_f32_e32 v50, v50, v187
	s_waitcnt lgkmcnt(1)
	v_mfma_f32_32x32x16_bf16 v[2:17], v[110:113], v[64:67], v[2:17]
	v_cvt_pk_bf16_f32 v60, v198, v199
	v_cvt_pk_bf16_f32 v61, v200, v201
	v_cvt_pk_bf16_f32 v62, v122, v123
	v_cvt_pk_bf16_f32 v63, v124, v125
	v_add_f32_e32 v50, v50, v194
	v_add_f32_e32 v50, v50, v195
	v_add_f32_e32 v50, v50, v196
	v_add_f32_e32 v50, v50, v197
	s_nop 0
	v_mfma_f32_32x32x16_bf16 v[18:33], v[106:109], v[60:63], v[18:33]
	v_add_f32_e32 v50, v50, v198
	v_add_f32_e32 v50, v50, v199
	v_add_f32_e32 v50, v50, v200
	v_add_f32_e32 v50, v50, v201
	s_waitcnt lgkmcnt(0)
	v_mfma_f32_32x32x16_bf16 v[2:17], v[114:117], v[60:63], v[2:17]
	v_add_f32_e32 v50, v50, v122
	v_add_f32_e32 v50, v50, v123
	v_add_f32_e32 v50, v50, v124
	v_add_f32_e32 v50, v50, v125
	s_setprio 2
	s_waitcnt lgkmcnt(0)
	s_barrier
	ds_read_b128 v[240:243], v165
	ds_read_b128 v[244:247], v165 offset:4608
	ds_read_b128 v[68:71], v165 offset:32
	ds_read_b128 v[72:75], v165 offset:4640
	v_add_f32_e32 v1, v1, v176
	v_exp_f32_e32 v176, v138
	v_exp_f32_e32 v177, v139
	v_exp_f32_e32 v178, v140
	v_exp_f32_e32 v179, v141
	v_exp_f32_e32 v185, v142
	v_exp_f32_e32 v186, v143
	v_exp_f32_e32 v187, v144
	v_exp_f32_e32 v194, v145
	s_waitcnt lgkmcnt(2)
	v_mfma_f32_32x32x16_bf16 v[122:137], v[240:243], v[158:161], v[34:49]
	v_mfma_f32_32x32x16_bf16 v[106:121], v[244:247], v[158:161], v[34:49]
	v_exp_f32_e32 v195, v146
	v_exp_f32_e32 v196, v147
	v_exp_f32_e32 v197, v148
	v_exp_f32_e32 v198, v149
	v_exp_f32_e32 v146, v150
	v_exp_f32_e32 v147, v151
	v_exp_f32_e32 v148, v152
	v_exp_f32_e32 v149, v153
	s_waitcnt lgkmcnt(1)
	v_mfma_f32_32x32x16_bf16 v[122:137], v[68:71], v[154:157], v[122:137]
	v_exp_f32_e32 v150, v82
	v_exp_f32_e32 v151, v83
	v_exp_f32_e32 v152, v84
	v_exp_f32_e32 v153, v85
	v_exp_f32_e32 v199, v86
	v_exp_f32_e32 v200, v87
	v_exp_f32_e32 v201, v88
	v_exp_f32_e32 v202, v89
	s_waitcnt lgkmcnt(0)
	v_mfma_f32_32x32x16_bf16 v[106:121], v[72:75], v[154:157], v[106:121]
	v_exp_f32_e32 v203, v90
	v_exp_f32_e32 v204, v91
	v_exp_f32_e32 v205, v92
	v_exp_f32_e32 v206, v93
	v_exp_f32_e32 v207, v94
	v_exp_f32_e32 v208, v95
	v_exp_f32_e32 v209, v96
	v_exp_f32_e32 v210, v97
	v_add_u32_e32 v88, s27, v163
	ds_read_b128 v[240:243], v165 offset:9216
	ds_read_b128 v[244:247], v165 offset:13824
	ds_read_b128 v[60:63], v88 offset:41472
	ds_read_b128 v[64:67], v88 offset:36864
	ds_read_b128 v[68:71], v88 offset:36896
	ds_read_b128 v[72:75], v88 offset:41504
	ds_read_b128 v[76:79], v88 offset:36928
	ds_read_b128 v[80:83], v88 offset:41536
	ds_read_b128 v[84:87], v88 offset:36960
	ds_read_b128 v[88:91], v88 offset:41568
	s_cmp_gt_i32 s25, 2
	s_cselect_b32 s28, -3, 2
	s_add_i32 s28, s28, s25
	s_mulk_i32 s28, 0x2400
	s_min_u32 s27, s23, s13
	v_add_u32_e32 v51, s28, v182
	s_lshl_b32 s92, s27, 13
	s_waitcnt vmcnt(3)
	ds_write_b128 v182, v[98:101] offset:18432
	s_waitcnt vmcnt(2)
	ds_write_b128 v51, v[102:105] offset:36864
	v_add_f32_e32 v1, v1, v50
	s_add_u32 vcc_lo, s100, s92
	s_addc_u32 vcc_hi, s101, 0
	global_load_dwordx4 v[138:141], v248, vcc
	s_lshl_b32 s92, s26, 7
	s_add_u32 vcc_lo, s98, s92
	s_addc_u32 vcc_hi, s99, 0
	global_load_dwordx4 v[142:145], v249, vcc
	s_setprio 1
	v_mov_b32_e32 v51, v122
	v_cvt_pk_bf16_f32 v92, v176, v177
	v_cvt_pk_bf16_f32 v93, v178, v179
	v_cvt_pk_bf16_f32 v94, v185, v186
	v_cvt_pk_bf16_f32 v95, v187, v194
	s_waitcnt lgkmcnt(8)
	s_nop 0
	v_mfma_f32_32x32x16_bf16 v[18:33], v[64:67], v[92:95], v[18:33]
	v_max3_f32 v51, v51, v123, v124
	v_max3_f32 v51, v51, v125, v126
	v_add_f32_e32 v50, v176, v177
	v_add_f32_e32 v50, v50, v178
	v_add_f32_e32 v50, v50, v179
	s_nop 0
	v_mfma_f32_32x32x16_bf16 v[2:17], v[60:63], v[92:95], v[2:17]
	v_cvt_pk_bf16_f32 v64, v195, v196
	v_cvt_pk_bf16_f32 v65, v197, v198
	v_cvt_pk_bf16_f32 v66, v146, v147
	v_cvt_pk_bf16_f32 v67, v148, v149
	v_max3_f32 v51, v51, v127, v128
	v_max3_f32 v51, v51, v129, v130
	v_add_f32_e32 v50, v50, v185
	v_add_f32_e32 v50, v50, v186
	v_add_f32_e32 v50, v50, v187
	v_add_f32_e32 v50, v50, v194
	s_waitcnt lgkmcnt(7)
	v_mfma_f32_32x32x16_bf16 v[18:33], v[68:71], v[64:67], v[18:33]
	v_max3_f32 v51, v51, v131, v132
	v_max3_f32 v51, v51, v133, v134
	v_add_f32_e32 v50, v50, v195
	v_add_f32_e32 v50, v50, v196
	v_add_f32_e32 v50, v50, v197
	v_add_f32_e32 v50, v50, v198
	s_waitcnt lgkmcnt(6)
	v_mfma_f32_32x32x16_bf16 v[2:17], v[72:75], v[64:67], v[2:17]
	v_cvt_pk_bf16_f32 v60, v150, v151
	v_cvt_pk_bf16_f32 v61, v152, v153
	v_cvt_pk_bf16_f32 v62, v199, v200
	v_cvt_pk_bf16_f32 v63, v201, v202
	v_max3_f32 v51, v51, v135, v136
	v_max3_f32 v51, v51, v137, v106
	v_add_f32_e32 v50, v50, v146
	v_add_f32_e32 v50, v50, v147
	v_add_f32_e32 v50, v50, v148
	v_add_f32_e32 v50, v50, v149
	s_waitcnt lgkmcnt(5)
	v_mfma_f32_32x32x16_bf16 v[18:33], v[76:79], v[60:63], v[18:33]
	v_max3_f32 v51, v51, v107, v108
	v_max3_f32 v51, v51, v109, v110
	v_add_f32_e32 v50, v50, v150
	v_add_f32_e32 v50, v50, v151
	v_add_f32_e32 v50, v50, v152
	v_add_f32_e32 v50, v50, v153
	s_waitcnt lgkmcnt(4)
	v_mfma_f32_32x32x16_bf16 v[2:17], v[80:83], v[60:63], v[2:17]
	v_cvt_pk_bf16_f32 v64, v203, v204
	v_cvt_pk_bf16_f32 v65, v205, v206
	v_cvt_pk_bf16_f32 v66, v207, v208
	v_cvt_pk_bf16_f32 v67, v209, v210
	v_max3_f32 v51, v51, v111, v112
	v_max3_f32 v51, v51, v113, v114
	v_add_f32_e32 v50, v50, v199
	v_add_f32_e32 v50, v50, v200
	v_add_f32_e32 v50, v50, v201
	v_add_f32_e32 v50, v50, v202
	s_waitcnt lgkmcnt(3)
	v_mfma_f32_32x32x16_bf16 v[18:33], v[84:87], v[64:67], v[18:33]
	v_max3_f32 v51, v51, v115, v116
	v_max3_f32 v51, v51, v117, v118
	v_add_f32_e32 v50, v50, v203
	v_add_f32_e32 v50, v50, v204
	v_add_f32_e32 v50, v50, v205
	v_add_f32_e32 v50, v50, v206
	s_waitcnt lgkmcnt(2)
	v_mfma_f32_32x32x16_bf16 v[2:17], v[88:91], v[64:67], v[2:17]
	v_max3_f32 v51, v51, v119, v120
	v_max3_f32 v51, v51, v121, v121
	v_add_f32_e32 v50, v50, v207
	v_add_f32_e32 v50, v50, v208
	v_add_f32_e32 v50, v50, v209
	v_add_f32_e32 v50, v50, v210
	s_setprio 0
	ds_read_b128 v[146:149], v165 offset:9248
	ds_read_b128 v[60:63], v165 offset:13856
	v_add_f32_e32 v50, v1, v50
	v_mov_b32_e32 v1, v51
	s_nop 1
	v_permlane32_swap_b32_e32 v51, v1
	v_max_f32_e32 v1, v1, v1
	v_max_f32_e32 v51, v51, v51
	v_max_f32_e32 v1, v51, v1
	v_cmp_lt_f32_e32 vcc, s52, v1
	s_cbranch_vccz .LBB0_643
	v_max_f32_e32 v1, v1, v1
	v_max_f32_e32 v68, 0, v1
	v_add_f32_e32 v183, v183, v68
	v_xor_b32_e32 v34, 0x80000000, v183
	v_pk_add_f32 v[122:123], v[122:123], v[68:69] op_sel_hi:[1,0] neg_lo:[0,1] neg_hi:[0,1]
	v_pk_add_f32 v[106:107], v[106:107], v[68:69] op_sel_hi:[1,0] neg_lo:[0,1] neg_hi:[0,1]
	v_pk_add_f32 v[124:125], v[124:125], v[68:69] op_sel_hi:[1,0] neg_lo:[0,1] neg_hi:[0,1]
	v_pk_add_f32 v[108:109], v[108:109], v[68:69] op_sel_hi:[1,0] neg_lo:[0,1] neg_hi:[0,1]
	v_pk_add_f32 v[126:127], v[126:127], v[68:69] op_sel_hi:[1,0] neg_lo:[0,1] neg_hi:[0,1]
	v_pk_add_f32 v[110:111], v[110:111], v[68:69] op_sel_hi:[1,0] neg_lo:[0,1] neg_hi:[0,1]
	v_pk_add_f32 v[128:129], v[128:129], v[68:69] op_sel_hi:[1,0] neg_lo:[0,1] neg_hi:[0,1]
	v_pk_add_f32 v[112:113], v[112:113], v[68:69] op_sel_hi:[1,0] neg_lo:[0,1] neg_hi:[0,1]
	v_pk_add_f32 v[130:131], v[130:131], v[68:69] op_sel_hi:[1,0] neg_lo:[0,1] neg_hi:[0,1]
	v_pk_add_f32 v[114:115], v[114:115], v[68:69] op_sel_hi:[1,0] neg_lo:[0,1] neg_hi:[0,1]
	v_pk_add_f32 v[132:133], v[132:133], v[68:69] op_sel_hi:[1,0] neg_lo:[0,1] neg_hi:[0,1]
	v_pk_add_f32 v[116:117], v[116:117], v[68:69] op_sel_hi:[1,0] neg_lo:[0,1] neg_hi:[0,1]
	v_pk_add_f32 v[134:135], v[134:135], v[68:69] op_sel_hi:[1,0] neg_lo:[0,1] neg_hi:[0,1]
	v_pk_add_f32 v[118:119], v[118:119], v[68:69] op_sel_hi:[1,0] neg_lo:[0,1] neg_hi:[0,1]
	v_pk_add_f32 v[136:137], v[136:137], v[68:69] op_sel_hi:[1,0] neg_lo:[0,1] neg_hi:[0,1]
	v_pk_add_f32 v[120:121], v[120:121], v[68:69] op_sel_hi:[1,0] neg_lo:[0,1] neg_hi:[0,1]
	v_exp_f32_e64 v68, -v68
	v_mov_b32_e32 v35, v34
	v_mov_b32_e32 v36, v34
	v_mov_b32_e32 v37, v34
	v_mov_b32_e32 v38, v34
	v_mov_b32_e32 v39, v34
	v_mov_b32_e32 v40, v34
	v_mov_b32_e32 v41, v34
	v_mov_b32_e32 v42, v34
	v_mov_b32_e32 v43, v34
	v_mov_b32_e32 v44, v34
	v_mov_b32_e32 v45, v34
	v_mov_b32_e32 v46, v34
	v_mov_b32_e32 v47, v34
	v_mov_b32_e32 v48, v34
	v_mov_b32_e32 v49, v34
	s_nop 11
	v_pk_mul_f32 v[32:33], v[32:33], v[68:69] op_sel_hi:[1,0]
	v_pk_mul_f32 v[30:31], v[30:31], v[68:69] op_sel_hi:[1,0]
	v_pk_mul_f32 v[28:29], v[28:29], v[68:69] op_sel_hi:[1,0]
	v_pk_mul_f32 v[26:27], v[26:27], v[68:69] op_sel_hi:[1,0]
	v_pk_mul_f32 v[24:25], v[24:25], v[68:69] op_sel_hi:[1,0]
	v_pk_mul_f32 v[22:23], v[22:23], v[68:69] op_sel_hi:[1,0]
	v_pk_mul_f32 v[20:21], v[20:21], v[68:69] op_sel_hi:[1,0]
	v_pk_mul_f32 v[18:19], v[18:19], v[68:69] op_sel_hi:[1,0]
	v_pk_mul_f32 v[16:17], v[16:17], v[68:69] op_sel_hi:[1,0]
	v_pk_mul_f32 v[14:15], v[14:15], v[68:69] op_sel_hi:[1,0]
	v_pk_mul_f32 v[12:13], v[12:13], v[68:69] op_sel_hi:[1,0]
	v_pk_mul_f32 v[10:11], v[10:11], v[68:69] op_sel_hi:[1,0]
	v_pk_mul_f32 v[8:9], v[8:9], v[68:69] op_sel_hi:[1,0]
	v_pk_mul_f32 v[6:7], v[6:7], v[68:69] op_sel_hi:[1,0]
	v_pk_mul_f32 v[4:5], v[4:5], v[68:69] op_sel_hi:[1,0]
	v_pk_mul_f32 v[2:3], v[2:3], v[68:69] op_sel_hi:[1,0]
	v_mul_f32_e32 v50, v50, v68

.LBB0_661:
	s_add_i32 s26, s13, -7
	s_lshl_b32 s92, s26, 13
	s_add_u32 vcc_lo, s100, s92
	s_addc_u32 vcc_hi, s101, 0
	global_load_dwordx4 v[2:5], v248, vcc
	s_add_i32 s26, s13, -8
	s_lshl_b32 s92, s26, 7
	s_add_u32 vcc_lo, s98, s92
	s_addc_u32 vcc_hi, s99, 0
	global_load_dwordx4 v[6:9], v249, vcc
	s_mul_i32 s28, s27, 0x2400
	s_add_i32 s26, s13, -7
	s_add_i32 s29, s28, 0xffffdc00
	s_cmp_lg_u32 s27, 0
	s_cselect_b32 s29, s29, 0x9000
	v_add_u32_e32 v1, s29, v195
	ds_read_b128 v[10:13], v1 offset:36864
	ds_read_b128 v[66:69], v1 offset:36896
	ds_read_b128 v[70:73], v1 offset:41472
	ds_read_b128 v[74:77], v1 offset:41504
	ds_read_b128 v[128:131], v1 offset:36928
	ds_read_b128 v[132:135], v1 offset:36960
	ds_read_b128 v[148:151], v1 offset:41536
	ds_read_b128 v[160:163], v1 offset:41568
	s_setprio 3
	v_cvt_pk_bf16_f32 v210, v116, v117
	v_cvt_pk_bf16_f32 v211, v118, v119
	v_cvt_pk_bf16_f32 v212, v112, v113
	v_cvt_pk_bf16_f32 v213, v114, v115
	s_waitcnt lgkmcnt(7)
	s_nop 0
	v_mfma_f32_32x32x16_bf16 v[16:31], v[10:13], v[210:213], v[16:31]
	v_add_f32_e32 v1, v116, v117
	v_add_f32_e32 v1, v1, v118
	v_add_f32_e32 v1, v1, v119
	s_waitcnt lgkmcnt(5)
	v_mfma_f32_32x32x16_bf16 v[32:47], v[70:73], v[210:213], v[32:47]
	v_cvt_pk_bf16_f32 v10, v187, v186
	v_cvt_pk_bf16_f32 v11, v185, v184
	v_cvt_pk_bf16_f32 v12, v147, v146
	v_cvt_pk_bf16_f32 v13, v145, v144
	v_add_f32_e32 v1, v1, v112
	v_add_f32_e32 v1, v1, v113
	v_add_f32_e32 v1, v1, v114
	v_add_f32_e32 v1, v1, v115
	s_nop 0
	v_mfma_f32_32x32x16_bf16 v[16:31], v[66:69], v[10:13], v[16:31]
	v_add_f32_e32 v1, v1, v187
	v_add_f32_e32 v1, v1, v186
	v_add_f32_e32 v1, v1, v185
	v_add_f32_e32 v1, v1, v184
	s_waitcnt lgkmcnt(4)
	v_mfma_f32_32x32x16_bf16 v[32:47], v[74:77], v[10:13], v[32:47]
	v_cvt_pk_bf16_f32 v66, v143, v142
	v_cvt_pk_bf16_f32 v67, v141, v140
	v_cvt_pk_bf16_f32 v68, v139, v138
	v_cvt_pk_bf16_f32 v69, v137, v136
	v_add_f32_e32 v1, v1, v147
	v_add_f32_e32 v1, v1, v146
	v_add_f32_e32 v1, v1, v145
	v_add_f32_e32 v1, v1, v144
	s_waitcnt lgkmcnt(3)
	v_mfma_f32_32x32x16_bf16 v[16:31], v[128:131], v[66:69], v[16:31]
	v_add_f32_e32 v1, v1, v143
	v_add_f32_e32 v1, v1, v142
	v_add_f32_e32 v1, v1, v141
	v_add_f32_e32 v1, v1, v140
	s_waitcnt lgkmcnt(1)
	v_mfma_f32_32x32x16_bf16 v[32:47], v[148:151], v[66:69], v[32:47]
	v_cvt_pk_bf16_f32 v10, v123, v122
	v_cvt_pk_bf16_f32 v11, v121, v120
	v_cvt_pk_bf16_f32 v12, v127, v126
	v_cvt_pk_bf16_f32 v13, v125, v124
	v_add_f32_e32 v1, v1, v139
	v_add_f32_e32 v1, v1, v138
	v_add_f32_e32 v1, v1, v137
	v_add_f32_e32 v1, v1, v136
	s_nop 0
	v_mfma_f32_32x32x16_bf16 v[16:31], v[132:135], v[10:13], v[16:31]
	v_add_f32_e32 v1, v1, v123
	v_add_f32_e32 v1, v1, v122
	v_add_f32_e32 v1, v1, v121
	v_add_f32_e32 v1, v1, v120
	s_waitcnt lgkmcnt(0)
	v_mfma_f32_32x32x16_bf16 v[32:47], v[160:163], v[10:13], v[32:47]
	v_add_f32_e32 v1, v1, v127
	v_add_f32_e32 v1, v1, v126
	v_add_f32_e32 v1, v1, v125
	v_add_f32_e32 v1, v1, v124
	s_setprio 2
	s_waitcnt lgkmcnt(0)
	s_barrier
	ds_read_b128 v[240:243], v195 offset:18432
	ds_read_b128 v[244:247], v195 offset:23040
	ds_read_b128 v[66:69], v195 offset:18464
	ds_read_b128 v[74:77], v195 offset:23072
	ds_read_b128 v[144:147], v195 offset:18496
	ds_read_b128 v[148:151], v195 offset:18528
	ds_read_b128 v[160:163], v195 offset:23104
	ds_read_b128 v[184:187], v195 offset:23136
	v_exp_f32_e32 v166, v96
	v_exp_f32_e32 v167, v97
	v_exp_f32_e32 v210, v98
	v_exp_f32_e32 v211, v99
	s_waitcnt lgkmcnt(6)
	v_mfma_f32_32x32x16_bf16 v[128:143], v[240:243], v[180:183], v[48:63]
	s_waitcnt lgkmcnt(5)
	v_mfma_f32_32x32x16_bf16 v[112:127], v[244:247], v[180:183], v[48:63]
	v_exp_f32_e32 v212, v100
	v_exp_f32_e32 v213, v101
	v_exp_f32_e32 v214, v102
	v_exp_f32_e32 v215, v103
	v_mfma_f32_32x32x16_bf16 v[128:143], v[66:69], v[176:179], v[128:143]
	v_exp_f32_e32 v100, v104
	v_exp_f32_e32 v101, v105
	v_exp_f32_e32 v102, v106
	v_exp_f32_e32 v103, v107
	s_waitcnt lgkmcnt(4)
	v_mfma_f32_32x32x16_bf16 v[112:127], v[74:77], v[176:179], v[112:127]
	v_exp_f32_e32 v104, v108
	v_exp_f32_e32 v105, v109
	v_exp_f32_e32 v106, v110
	v_exp_f32_e32 v107, v111
	s_waitcnt lgkmcnt(3)
	v_mfma_f32_32x32x16_bf16 v[128:143], v[144:147], v[172:175], v[128:143]
	v_exp_f32_e32 v108, v80
	v_exp_f32_e32 v109, v81
	v_exp_f32_e32 v110, v82
	v_exp_f32_e32 v111, v83
	s_waitcnt lgkmcnt(1)
	v_mfma_f32_32x32x16_bf16 v[112:127], v[160:163], v[172:175], v[112:127]
	v_exp_f32_e32 v144, v84
	v_exp_f32_e32 v145, v85
	v_exp_f32_e32 v146, v86
	v_exp_f32_e32 v147, v87
	v_mfma_f32_32x32x16_bf16 v[128:143], v[148:151], v[168:171], v[128:143]
	v_exp_f32_e32 v216, v88
	v_exp_f32_e32 v217, v89
	v_exp_f32_e32 v218, v90
	v_exp_f32_e32 v219, v91
	s_waitcnt lgkmcnt(0)
	v_mfma_f32_32x32x16_bf16 v[112:127], v[184:187], v[168:171], v[112:127]
	v_exp_f32_e32 v148, v92
	v_exp_f32_e32 v149, v93
	v_exp_f32_e32 v150, v94
	v_exp_f32_e32 v151, v95
	v_add_f32_e32 v1, v64, v1
	v_add_u32_e32 v92, s28, v195
	ds_read_b128 v[240:243], v195 offset:27648
	ds_read_b128 v[244:247], v195 offset:32256
	ds_read_b128 v[64:67], v92 offset:41472
	ds_read_b128 v[68:71], v92 offset:36864
	ds_read_b128 v[72:75], v92 offset:36896
	ds_read_b128 v[76:79], v92 offset:41504
	ds_read_b128 v[80:83], v92 offset:36928
	ds_read_b128 v[84:87], v92 offset:41536
	ds_read_b128 v[88:91], v92 offset:36960
	ds_read_b128 v[92:95], v92 offset:41568
	s_cmp_gt_i32 s27, 2
	s_cselect_b32 s29, -3, 2
	s_add_i32 s29, s29, s27
	s_add_i32 s28, s13, -6
	s_mulk_i32 s29, 0x2400
	s_min_u32 s28, s28, s12
	v_add_u32_e32 v10, s29, v208
	s_min_u32 s26, s26, s12
	s_lshl_b32 s92, s28, 13
	s_waitcnt vmcnt(3)
	ds_write_b128 v208, v[152:155]
	s_waitcnt vmcnt(2)
	ds_write_b128 v10, v[156:159] offset:36864
	s_add_u32 vcc_lo, s100, s92
	s_addc_u32 vcc_hi, s101, 0
	global_load_dwordx4 v[10:13], v248, vcc
	s_lshl_b32 s92, s26, 7
	s_add_u32 vcc_lo, s98, s92
	s_addc_u32 vcc_hi, s99, 0
	global_load_dwordx4 v[160:163], v249, vcc
	s_add_i32 s29, s27, 1
	s_setprio 1
	v_cvt_pk_bf16_f32 v96, v166, v167
	v_cvt_pk_bf16_f32 v97, v210, v211
	v_cvt_pk_bf16_f32 v98, v212, v213
	v_cvt_pk_bf16_f32 v99, v214, v215
	s_waitcnt lgkmcnt(8)
	s_nop 0
	v_mfma_f32_32x32x16_bf16 v[16:31], v[68:71], v[96:99], v[16:31]
	v_add_f32_e32 v184, v166, v167
	v_add_f32_e32 v184, v184, v210
	v_add_f32_e32 v184, v184, v211
	s_nop 0
	v_mfma_f32_32x32x16_bf16 v[32:47], v[64:67], v[96:99], v[32:47]
	v_cvt_pk_bf16_f32 v68, v100, v101
	v_cvt_pk_bf16_f32 v69, v102, v103
	v_cvt_pk_bf16_f32 v70, v104, v105
	v_cvt_pk_bf16_f32 v71, v106, v107
	v_add_f32_e32 v184, v184, v212
	v_add_f32_e32 v184, v184, v213
	v_add_f32_e32 v184, v184, v214
	v_add_f32_e32 v184, v184, v215
	s_waitcnt lgkmcnt(7)
	v_mfma_f32_32x32x16_bf16 v[16:31], v[72:75], v[68:71], v[16:31]
	v_add_f32_e32 v184, v184, v100
	v_add_f32_e32 v184, v184, v101
	v_add_f32_e32 v184, v184, v102
	v_add_f32_e32 v184, v184, v103
	s_waitcnt lgkmcnt(6)
	v_mfma_f32_32x32x16_bf16 v[32:47], v[76:79], v[68:71], v[32:47]
	v_cvt_pk_bf16_f32 v64, v108, v109
	v_cvt_pk_bf16_f32 v65, v110, v111
	v_cvt_pk_bf16_f32 v66, v144, v145
	v_cvt_pk_bf16_f32 v67, v146, v147
	v_add_f32_e32 v184, v184, v104
	v_add_f32_e32 v184, v184, v105
	v_add_f32_e32 v184, v184, v106
	v_add_f32_e32 v184, v184, v107
	s_waitcnt lgkmcnt(5)
	v_mfma_f32_32x32x16_bf16 v[16:31], v[80:83], v[64:67], v[16:31]
	v_add_f32_e32 v184, v184, v108
	v_add_f32_e32 v184, v184, v109
	v_add_f32_e32 v184, v184, v110
	v_add_f32_e32 v184, v184, v111
	s_waitcnt lgkmcnt(4)
	v_mfma_f32_32x32x16_bf16 v[32:47], v[84:87], v[64:67], v[32:47]
	v_cvt_pk_bf16_f32 v68, v216, v217
	v_cvt_pk_bf16_f32 v69, v218, v219
	v_cvt_pk_bf16_f32 v70, v148, v149
	v_cvt_pk_bf16_f32 v71, v150, v151
	v_add_f32_e32 v184, v184, v144
	v_add_f32_e32 v184, v184, v145
	v_add_f32_e32 v184, v184, v146
	v_add_f32_e32 v184, v184, v147
	s_waitcnt lgkmcnt(3)
	v_mfma_f32_32x32x16_bf16 v[16:31], v[88:91], v[68:71], v[16:31]
	v_add_f32_e32 v184, v184, v216
	v_add_f32_e32 v184, v184, v217
	v_add_f32_e32 v184, v184, v218
	v_add_f32_e32 v184, v184, v219
	s_waitcnt lgkmcnt(2)
	v_mfma_f32_32x32x16_bf16 v[32:47], v[92:95], v[68:71], v[32:47]
	v_add_f32_e32 v184, v184, v148
	v_add_f32_e32 v184, v184, v149
	v_add_f32_e32 v184, v184, v150
	v_add_f32_e32 v184, v184, v151
	s_setprio 0
	ds_read_b128 v[68:71], v195 offset:27680
	ds_read_b128 v[76:79], v195 offset:32288
	ds_read_b128 v[80:83], v195 offset:27712
	ds_read_b128 v[84:87], v195 offset:27744
	ds_read_b128 v[88:91], v195 offset:32320
	ds_read_b128 v[92:95], v195 offset:32352
	s_cmp_lg_u32 s27, 4
	s_cselect_b32 s26, s29, 0
	s_waitcnt lgkmcnt(6)
	v_mfma_f32_32x32x16_bf16 v[144:159], v[240:243], v[180:183], v[48:63]
	v_exp_f32_e32 v166, v128
	v_exp_f32_e32 v167, v129
	v_exp_f32_e32 v185, v130
	v_exp_f32_e32 v186, v131
	s_waitcnt lgkmcnt(5)
	v_mfma_f32_32x32x16_bf16 v[96:111], v[244:247], v[180:183], v[48:63]
	v_exp_f32_e32 v128, v132
	v_exp_f32_e32 v129, v133
	v_exp_f32_e32 v130, v134
	v_exp_f32_e32 v131, v135
	v_mfma_f32_32x32x16_bf16 v[144:159], v[68:71], v[176:179], v[144:159]
	v_exp_f32_e32 v132, v136
	v_exp_f32_e32 v133, v137
	v_exp_f32_e32 v134, v138
	v_exp_f32_e32 v135, v139
	s_waitcnt lgkmcnt(4)
	v_mfma_f32_32x32x16_bf16 v[96:111], v[76:79], v[176:179], v[96:111]
	v_exp_f32_e32 v136, v140
	v_exp_f32_e32 v137, v141
	v_exp_f32_e32 v138, v142
	v_exp_f32_e32 v139, v143
	s_waitcnt lgkmcnt(3)
	v_mfma_f32_32x32x16_bf16 v[144:159], v[80:83], v[172:175], v[144:159]
	v_exp_f32_e32 v140, v112
	v_exp_f32_e32 v141, v113
	v_exp_f32_e32 v142, v114
	v_exp_f32_e32 v143, v115
	s_waitcnt lgkmcnt(1)
	v_mfma_f32_32x32x16_bf16 v[96:111], v[88:91], v[172:175], v[96:111]
	v_exp_f32_e32 v187, v116
	v_exp_f32_e32 v210, v117
	v_exp_f32_e32 v211, v118
	v_exp_f32_e32 v212, v119
	v_mfma_f32_32x32x16_bf16 v[144:159], v[84:87], v[168:171], v[144:159]
	v_exp_f32_e32 v116, v120
	v_exp_f32_e32 v117, v121
	v_exp_f32_e32 v118, v122
	v_exp_f32_e32 v119, v123
	s_waitcnt lgkmcnt(0)
	v_mfma_f32_32x32x16_bf16 v[96:111], v[92:95], v[168:171], v[96:111]
	v_exp_f32_e32 v120, v124
	v_exp_f32_e32 v121, v125
	v_exp_f32_e32 v122, v126
	v_exp_f32_e32 v123, v127
	s_mul_i32 vcc_lo, s26, 0x2400
	v_add_u32_e32 v251, vcc_lo, v195
	ds_read_b128 v[240:243], v251 offset:36864
	ds_read_b128 v[244:247], v251 offset:41472
	s_cmp_gt_i32 s26, 2
	s_cselect_b32 s27, -3, 2
	s_add_i32 s27, s27, s26
	s_mulk_i32 s27, 0x2400
	s_waitcnt vmcnt(3)
	ds_write_b128 v208, v[2:5] offset:9216
	v_add_u32_e32 v2, s27, v208
	s_add_i32 s27, s26, 1
	s_cmp_lg_u32 s26, 4
	s_cselect_b32 s26, s27, 0
	s_add_i32 s27, s13, -5
	s_min_u32 s27, s27, s12
	s_lshl_b32 s92, s27, 13
	s_waitcnt vmcnt(2)
	ds_write_b128 v2, v[6:9] offset:36864
	s_add_u32 vcc_lo, s100, s92
	s_addc_u32 vcc_hi, s101, 0
	global_load_dwordx4 v[6:9], v248, vcc
	s_lshl_b32 s92, s28, 7
	s_add_u32 vcc_lo, s98, s92
	s_addc_u32 vcc_hi, s99, 0
	global_load_dwordx4 v[2:5], v249, vcc
	s_nop 0
	s_mul_i32 s28, s26, 0x2400
	s_add_i32 s29, s28, 0xffffdc00
	s_cmp_lg_u32 s26, 0
	s_cselect_b32 s29, s29, 0x9000
	v_add_u32_e32 v92, s29, v195
	ds_read_b128 v[68:71], v92 offset:36896
	ds_read_b128 v[76:79], v92 offset:41504
	ds_read_b128 v[80:83], v92 offset:36928
	ds_read_b128 v[84:87], v92 offset:36960
	ds_read_b128 v[88:91], v92 offset:41536
	ds_read_b128 v[92:95], v92 offset:41568
	s_setprio 3
	v_cvt_pk_bf16_f32 v112, v166, v167
	v_cvt_pk_bf16_f32 v113, v185, v186
	v_cvt_pk_bf16_f32 v114, v128, v129
	v_cvt_pk_bf16_f32 v115, v130, v131
	s_waitcnt lgkmcnt(6)
	s_nop 0
	v_mfma_f32_32x32x16_bf16 v[16:31], v[240:243], v[112:115], v[16:31]
	v_add_f32_e32 v213, v166, v167
	v_add_f32_e32 v213, v213, v185
	v_add_f32_e32 v213, v213, v186
	v_mfma_f32_32x32x16_bf16 v[32:47], v[244:247], v[112:115], v[32:47]
	v_cvt_pk_bf16_f32 v64, v132, v133
	v_cvt_pk_bf16_f32 v65, v134, v135
	v_cvt_pk_bf16_f32 v66, v136, v137
	v_cvt_pk_bf16_f32 v67, v138, v139
	v_add_f32_e32 v213, v213, v128
	v_add_f32_e32 v213, v213, v129
	v_add_f32_e32 v213, v213, v130
	v_add_f32_e32 v213, v213, v131
	s_nop 0
	s_waitcnt lgkmcnt(5)
	v_mfma_f32_32x32x16_bf16 v[16:31], v[68:71], v[64:67], v[16:31]
	v_add_f32_e32 v213, v213, v132
	v_add_f32_e32 v213, v213, v133
	v_add_f32_e32 v213, v213, v134
	v_add_f32_e32 v213, v213, v135
	s_waitcnt lgkmcnt(4)
	v_mfma_f32_32x32x16_bf16 v[32:47], v[76:79], v[64:67], v[32:47]
	v_cvt_pk_bf16_f32 v68, v140, v141
	v_cvt_pk_bf16_f32 v69, v142, v143
	v_cvt_pk_bf16_f32 v70, v187, v210
	v_cvt_pk_bf16_f32 v71, v211, v212
	v_add_f32_e32 v213, v213, v136
	v_add_f32_e32 v213, v213, v137
	v_add_f32_e32 v213, v213, v138
	v_add_f32_e32 v213, v213, v139
	s_waitcnt lgkmcnt(3)
	v_mfma_f32_32x32x16_bf16 v[16:31], v[80:83], v[68:71], v[16:31]
	v_add_f32_e32 v213, v213, v140
	v_add_f32_e32 v213, v213, v141
	v_add_f32_e32 v213, v213, v142
	v_add_f32_e32 v213, v213, v143
	s_waitcnt lgkmcnt(1)
	v_mfma_f32_32x32x16_bf16 v[32:47], v[88:91], v[68:71], v[32:47]
	v_cvt_pk_bf16_f32 v64, v116, v117
	v_cvt_pk_bf16_f32 v65, v118, v119
	v_cvt_pk_bf16_f32 v66, v120, v121
	v_cvt_pk_bf16_f32 v67, v122, v123
	v_add_f32_e32 v213, v213, v187
	v_add_f32_e32 v213, v213, v210
	v_add_f32_e32 v213, v213, v211
	v_add_f32_e32 v213, v213, v212
	s_nop 0
	v_mfma_f32_32x32x16_bf16 v[16:31], v[84:87], v[64:67], v[16:31]
	v_add_f32_e32 v213, v213, v116
	v_add_f32_e32 v213, v213, v117
	v_add_f32_e32 v213, v213, v118
	v_add_f32_e32 v213, v213, v119
	s_waitcnt lgkmcnt(0)
	v_mfma_f32_32x32x16_bf16 v[32:47], v[92:95], v[64:67], v[32:47]
	v_add_f32_e32 v213, v213, v120
	v_add_f32_e32 v213, v213, v121
	v_add_f32_e32 v213, v213, v122
	v_add_f32_e32 v213, v213, v123
	s_setprio 2
	s_waitcnt lgkmcnt(0)
	s_barrier
	ds_read_b128 v[240:243], v195
	ds_read_b128 v[244:247], v195 offset:4608
	ds_read_b128 v[116:119], v195 offset:32
	ds_read_b128 v[120:123], v195 offset:4640
	ds_read_b128 v[124:127], v195 offset:64
	ds_read_b128 v[128:131], v195 offset:4672
	ds_read_b128 v[132:135], v195 offset:96
	ds_read_b128 v[136:139], v195 offset:4704
	v_add_f32_e32 v1, v1, v184
	v_exp_f32_e32 v140, v144
	v_exp_f32_e32 v141, v145
	v_exp_f32_e32 v142, v146
	v_exp_f32_e32 v143, v147
	s_waitcnt lgkmcnt(6)
	v_mfma_f32_32x32x16_bf16 v[80:95], v[240:243], v[180:183], v[48:63]
	v_mfma_f32_32x32x16_bf16 v[64:79], v[244:247], v[180:183], v[48:63]
	v_exp_f32_e32 v144, v148
	v_exp_f32_e32 v145, v149
	v_exp_f32_e32 v146, v150
	v_exp_f32_e32 v147, v151
	s_waitcnt lgkmcnt(5)
	v_mfma_f32_32x32x16_bf16 v[80:95], v[116:119], v[176:179], v[80:95]
	v_exp_f32_e32 v148, v152
	v_exp_f32_e32 v149, v153
	v_exp_f32_e32 v150, v154
	v_exp_f32_e32 v151, v155
	s_waitcnt lgkmcnt(4)
	v_mfma_f32_32x32x16_bf16 v[64:79], v[120:123], v[176:179], v[64:79]
	v_exp_f32_e32 v152, v156
	v_exp_f32_e32 v153, v157
	v_exp_f32_e32 v154, v158
	v_exp_f32_e32 v155, v159
	s_waitcnt lgkmcnt(3)
	v_mfma_f32_32x32x16_bf16 v[80:95], v[124:127], v[172:175], v[80:95]
	v_exp_f32_e32 v156, v96
	v_exp_f32_e32 v157, v97
	v_exp_f32_e32 v158, v98
	v_exp_f32_e32 v159, v99
	s_waitcnt lgkmcnt(2)
	v_mfma_f32_32x32x16_bf16 v[64:79], v[128:131], v[172:175], v[64:79]
	v_exp_f32_e32 v166, v100
	v_exp_f32_e32 v167, v101
	v_exp_f32_e32 v184, v102
	v_exp_f32_e32 v185, v103
	s_waitcnt lgkmcnt(1)
	v_mfma_f32_32x32x16_bf16 v[80:95], v[132:135], v[168:171], v[80:95]
	v_exp_f32_e32 v186, v104
	v_exp_f32_e32 v187, v105
	v_exp_f32_e32 v210, v106
	v_exp_f32_e32 v211, v107
	s_waitcnt lgkmcnt(0)
	v_mfma_f32_32x32x16_bf16 v[64:79], v[136:139], v[168:171], v[64:79]
	v_exp_f32_e32 v212, v108
	v_exp_f32_e32 v214, v109
	v_exp_f32_e32 v215, v110
	v_exp_f32_e32 v216, v111
	v_add_u32_e32 v124, s28, v195
	ds_read_b128 v[240:243], v195 offset:9216
	ds_read_b128 v[244:247], v195 offset:13824
	ds_read_b128 v[96:99], v124 offset:41472
	ds_read_b128 v[100:103], v124 offset:36864
	ds_read_b128 v[104:107], v124 offset:36896
	ds_read_b128 v[108:111], v124 offset:41504
	ds_read_b128 v[112:115], v124 offset:36928
	ds_read_b128 v[116:119], v124 offset:41536
	ds_read_b128 v[120:123], v124 offset:36960
	ds_read_b128 v[124:127], v124 offset:41568
	s_cmp_gt_i32 s26, 2
	s_cselect_b32 s29, -3, 2
	s_add_i32 s29, s29, s26
	s_mulk_i32 s29, 0x2400
	s_waitcnt vmcnt(3)
	ds_write_b128 v208, v[10:13] offset:18432
	v_add_u32_e32 v10, s29, v208
	s_mov_b32 s29, 0x1da90000
	s_waitcnt vmcnt(2)
	ds_write_b128 v10, v[160:163] offset:36864
	s_add_i32 s92, s13, -4
	s_lshl_b32 s92, s92, 13
	s_add_u32 vcc_lo, s100, s92
	s_addc_u32 vcc_hi, s101, 0
	global_load_dwordx4 v[128:131], v248, vcc
	s_lshl_b32 s92, s27, 7
	s_add_u32 vcc_lo, s98, s92
	s_addc_u32 vcc_hi, s99, 0
	global_load_dwordx4 v[10:13], v249, vcc
	v_add_f32_e32 v1, v1, v213
	s_add_i32 s28, s26, 1
	s_setprio 1
	v_cvt_pk_bf16_f32 v132, v140, v141
	v_cvt_pk_bf16_f32 v133, v142, v143
	v_cvt_pk_bf16_f32 v134, v144, v145
	v_cvt_pk_bf16_f32 v135, v146, v147
	s_waitcnt lgkmcnt(8)
	s_nop 0
	v_mfma_f32_32x32x16_bf16 v[16:31], v[100:103], v[132:135], v[16:31]
	v_add_f32_e32 v160, v140, v141
	v_add_f32_e32 v160, v160, v142
	v_add_f32_e32 v160, v160, v143
	s_nop 0
	v_mfma_f32_32x32x16_bf16 v[32:47], v[96:99], v[132:135], v[32:47]
	v_cvt_pk_bf16_f32 v100, v148, v149
	v_cvt_pk_bf16_f32 v101, v150, v151
	v_cvt_pk_bf16_f32 v102, v152, v153
	v_cvt_pk_bf16_f32 v103, v154, v155
	v_add_f32_e32 v160, v160, v144
	v_add_f32_e32 v160, v160, v145
	v_add_f32_e32 v160, v160, v146
	v_add_f32_e32 v160, v160, v147
	s_waitcnt lgkmcnt(7)
	v_mfma_f32_32x32x16_bf16 v[16:31], v[104:107], v[100:103], v[16:31]
	v_add_f32_e32 v160, v160, v148
	v_add_f32_e32 v160, v160, v149
	v_add_f32_e32 v160, v160, v150
	v_add_f32_e32 v160, v160, v151
	s_waitcnt lgkmcnt(6)
	v_mfma_f32_32x32x16_bf16 v[32:47], v[108:111], v[100:103], v[32:47]
	v_cvt_pk_bf16_f32 v96, v156, v157
	v_cvt_pk_bf16_f32 v97, v158, v159
	v_cvt_pk_bf16_f32 v98, v166, v167
	v_cvt_pk_bf16_f32 v99, v184, v185
	v_add_f32_e32 v160, v160, v152
	v_add_f32_e32 v160, v160, v153
	v_add_f32_e32 v160, v160, v154
	v_add_f32_e32 v160, v160, v155
	s_waitcnt lgkmcnt(5)
	v_mfma_f32_32x32x16_bf16 v[16:31], v[112:115], v[96:99], v[16:31]
	v_add_f32_e32 v160, v160, v156
	v_add_f32_e32 v160, v160, v157
	v_add_f32_e32 v160, v160, v158
	v_add_f32_e32 v160, v160, v159
	s_waitcnt lgkmcnt(4)
	v_mfma_f32_32x32x16_bf16 v[32:47], v[116:119], v[96:99], v[32:47]
	v_cvt_pk_bf16_f32 v100, v186, v187
	v_cvt_pk_bf16_f32 v101, v210, v211
	v_cvt_pk_bf16_f32 v102, v212, v214
	v_cvt_pk_bf16_f32 v103, v215, v216
	v_add_f32_e32 v160, v160, v166
	v_add_f32_e32 v160, v160, v167
	v_add_f32_e32 v160, v160, v184
	v_add_f32_e32 v160, v160, v185
	s_waitcnt lgkmcnt(3)
	v_mfma_f32_32x32x16_bf16 v[16:31], v[120:123], v[100:103], v[16:31]
	v_add_f32_e32 v160, v160, v186
	v_add_f32_e32 v160, v160, v187
	v_add_f32_e32 v160, v160, v210
	v_add_f32_e32 v160, v160, v211
	s_waitcnt lgkmcnt(2)
	v_mfma_f32_32x32x16_bf16 v[32:47], v[124:127], v[100:103], v[32:47]
	v_add_f32_e32 v160, v160, v212
	v_add_f32_e32 v160, v160, v214
	v_add_f32_e32 v160, v160, v215
	v_add_f32_e32 v160, v160, v216
	s_setprio 0
	ds_read_b128 v[132:135], v195 offset:9248
	ds_read_b128 v[140:143], v195 offset:13856
	ds_read_b128 v[144:147], v195 offset:9280
	ds_read_b128 v[148:151], v195 offset:9312
	ds_read_b128 v[152:155], v195 offset:13888
	ds_read_b128 v[156:159], v195 offset:13920
	s_cmp_lg_u32 s26, 4
	s_cselect_b32 s26, s28, 0
	s_waitcnt lgkmcnt(6)
	v_mfma_f32_32x32x16_bf16 v[112:127], v[240:243], v[180:183], v[48:63]
	v_exp_f32_e32 v161, v80
	v_exp_f32_e32 v162, v81
	v_exp_f32_e32 v163, v82
	v_exp_f32_e32 v164, v83
	s_waitcnt lgkmcnt(5)
	v_mfma_f32_32x32x16_bf16 v[96:111], v[244:247], v[180:183], v[48:63]
	v_exp_f32_e32 v165, v84
	v_exp_f32_e32 v166, v85
	v_exp_f32_e32 v167, v86
	v_exp_f32_e32 v184, v87
	v_mfma_f32_32x32x16_bf16 v[112:127], v[132:135], v[176:179], v[112:127]
	v_exp_f32_e32 v136, v88
	v_exp_f32_e32 v137, v89
	v_exp_f32_e32 v138, v90
	v_exp_f32_e32 v139, v91
	s_waitcnt lgkmcnt(4)
	v_mfma_f32_32x32x16_bf16 v[96:111], v[140:143], v[176:179], v[96:111]
	v_exp_f32_e32 v185, v92
	v_exp_f32_e32 v186, v93
	v_exp_f32_e32 v187, v94
	v_exp_f32_e32 v210, v95
	s_waitcnt lgkmcnt(3)
	v_mfma_f32_32x32x16_bf16 v[112:127], v[144:147], v[172:175], v[112:127]
	v_exp_f32_e32 v140, v64
	v_exp_f32_e32 v141, v65
	v_exp_f32_e32 v142, v66
	v_exp_f32_e32 v143, v67
	s_waitcnt lgkmcnt(1)
	v_mfma_f32_32x32x16_bf16 v[96:111], v[152:155], v[172:175], v[96:111]
	v_exp_f32_e32 v144, v68
	v_exp_f32_e32 v145, v69
	v_exp_f32_e32 v146, v70
	v_exp_f32_e32 v147, v71
	v_mfma_f32_32x32x16_bf16 v[112:127], v[148:151], v[168:171], v[112:127]
	v_exp_f32_e32 v152, v72
	v_exp_f32_e32 v153, v73
	v_exp_f32_e32 v154, v74
	v_exp_f32_e32 v155, v75
	s_waitcnt lgkmcnt(0)
	v_mfma_f32_32x32x16_bf16 v[96:111], v[156:159], v[168:171], v[96:111]
	v_exp_f32_e32 v148, v76
	v_exp_f32_e32 v149, v77
	v_exp_f32_e32 v150, v78
	v_exp_f32_e32 v151, v79
	s_mul_i32 vcc_lo, s26, 0x2400
	v_add_u32_e32 v251, vcc_lo, v195
	ds_read_b128 v[240:243], v251 offset:36864
	ds_read_b128 v[244:247], v251 offset:41472
	s_cmp_gt_i32 s26, 2
	s_cselect_b32 s27, -3, 2
	s_add_i32 s27, s27, s26
	s_mulk_i32 s27, 0x2400
	s_waitcnt vmcnt(3)
	ds_write_b128 v208, v[6:9] offset:27648
	v_add_u32_e32 v6, s27, v208
	s_add_i32 s27, s26, 1
	s_cmp_lg_u32 s26, 4
	s_cselect_b32 s27, s27, 0
	s_add_i32 s26, s13, -3
	s_min_u32 s28, s26, s12
	s_lshl_b32 s92, s28, 13
	s_waitcnt vmcnt(2)
	ds_write_b128 v6, v[2:5] offset:36864
	s_add_u32 vcc_lo, s100, s92
	s_addc_u32 vcc_hi, s101, 0
	global_load_dwordx4 v[6:9], v248, vcc
	s_nop 0
	s_add_i32 s92, s13, -4
	s_lshl_b32 s92, s92, 7
	s_add_u32 vcc_lo, s98, s92
	s_addc_u32 vcc_hi, s99, 0
	global_load_dwordx4 v[2:5], v249, vcc
	s_mul_i32 s29, s27, 0x2400
	s_add_i32 s34, s29, 0xffffdc00
	s_cmp_lg_u32 s27, 0
	s_cselect_b32 s34, s34, 0x9000
	v_add_u32_e32 v14, s34, v195
	ds_read_b128 v[68:71], v14 offset:36896
	ds_read_b128 v[76:79], v14 offset:41504
	ds_read_b128 v[80:83], v14 offset:36928
	ds_read_b128 v[84:87], v14 offset:36960
	ds_read_b128 v[88:91], v14 offset:41536
	ds_read_b128 v[92:95], v14 offset:41568
	s_setprio 3
	v_cvt_pk_bf16_f32 v132, v161, v162
	v_cvt_pk_bf16_f32 v133, v163, v164
	v_cvt_pk_bf16_f32 v134, v165, v166
	v_cvt_pk_bf16_f32 v135, v167, v184
	s_waitcnt lgkmcnt(6)
	s_nop 0
	v_mfma_f32_32x32x16_bf16 v[16:31], v[240:243], v[132:135], v[16:31]
	v_add_f32_e32 v14, v161, v162
	v_add_f32_e32 v14, v14, v163
	v_add_f32_e32 v14, v14, v164
	v_mfma_f32_32x32x16_bf16 v[32:47], v[244:247], v[132:135], v[32:47]
	v_cvt_pk_bf16_f32 v64, v136, v137
	v_cvt_pk_bf16_f32 v65, v138, v139
	v_cvt_pk_bf16_f32 v66, v185, v186
	v_cvt_pk_bf16_f32 v67, v187, v210
	v_add_f32_e32 v14, v14, v165
	v_add_f32_e32 v14, v14, v166
	v_add_f32_e32 v14, v14, v167
	v_add_f32_e32 v14, v14, v184
	s_nop 0
	s_waitcnt lgkmcnt(5)
	v_mfma_f32_32x32x16_bf16 v[16:31], v[68:71], v[64:67], v[16:31]
	v_add_f32_e32 v14, v14, v136
	v_add_f32_e32 v14, v14, v137
	v_add_f32_e32 v14, v14, v138
	v_add_f32_e32 v14, v14, v139
	s_waitcnt lgkmcnt(4)
	v_mfma_f32_32x32x16_bf16 v[32:47], v[76:79], v[64:67], v[32:47]
	v_cvt_pk_bf16_f32 v68, v140, v141
	v_cvt_pk_bf16_f32 v69, v142, v143
	v_cvt_pk_bf16_f32 v70, v144, v145
	v_cvt_pk_bf16_f32 v71, v146, v147
	v_add_f32_e32 v14, v14, v185
	v_add_f32_e32 v14, v14, v186
	v_add_f32_e32 v14, v14, v187
	v_add_f32_e32 v14, v14, v210
	s_waitcnt lgkmcnt(3)
	v_mfma_f32_32x32x16_bf16 v[16:31], v[80:83], v[68:71], v[16:31]
	v_add_f32_e32 v14, v14, v140
	v_add_f32_e32 v14, v14, v141
	v_add_f32_e32 v14, v14, v142
	v_add_f32_e32 v14, v14, v143
	s_waitcnt lgkmcnt(1)
	v_mfma_f32_32x32x16_bf16 v[32:47], v[88:91], v[68:71], v[32:47]
	v_cvt_pk_bf16_f32 v64, v152, v153
	v_cvt_pk_bf16_f32 v65, v154, v155
	v_cvt_pk_bf16_f32 v66, v148, v149
	v_cvt_pk_bf16_f32 v67, v150, v151
	v_add_f32_e32 v14, v14, v144
	v_add_f32_e32 v14, v14, v145
	v_add_f32_e32 v14, v14, v146
	v_add_f32_e32 v14, v14, v147
	s_nop 0
	v_mfma_f32_32x32x16_bf16 v[16:31], v[84:87], v[64:67], v[16:31]
	v_add_f32_e32 v14, v14, v152
	v_add_f32_e32 v14, v14, v153
	v_add_f32_e32 v14, v14, v154
	v_add_f32_e32 v14, v14, v155
	s_waitcnt lgkmcnt(0)
	v_mfma_f32_32x32x16_bf16 v[32:47], v[92:95], v[64:67], v[32:47]
	v_add_f32_e32 v14, v14, v148
	v_add_f32_e32 v14, v14, v149
	v_add_f32_e32 v14, v14, v150
	v_add_f32_e32 v14, v14, v151
	s_setprio 2
	s_waitcnt lgkmcnt(0)
	s_barrier
	ds_read_b128 v[240:243], v195 offset:18432
	ds_read_b128 v[244:247], v195 offset:23040
	ds_read_b128 v[136:139], v195 offset:18464
	ds_read_b128 v[140:143], v195 offset:23072
	ds_read_b128 v[144:147], v195 offset:18496
	ds_read_b128 v[148:151], v195 offset:23104
	ds_read_b128 v[152:155], v195 offset:18528
	ds_read_b128 v[156:159], v195 offset:23136
	v_add_f32_e32 v1, v1, v160
	v_exp_f32_e32 v160, v112
	v_exp_f32_e32 v161, v113
	v_exp_f32_e32 v162, v114
	v_exp_f32_e32 v163, v115
	s_waitcnt lgkmcnt(6)
	v_mfma_f32_32x32x16_bf16 v[80:95], v[240:243], v[180:183], v[48:63]
	v_mfma_f32_32x32x16_bf16 v[64:79], v[244:247], v[180:183], v[48:63]
	v_exp_f32_e32 v164, v116
	v_exp_f32_e32 v165, v117
	v_exp_f32_e32 v166, v118
	v_exp_f32_e32 v167, v119
	s_waitcnt lgkmcnt(5)
	v_mfma_f32_32x32x16_bf16 v[80:95], v[136:139], v[176:179], v[80:95]
	v_exp_f32_e32 v184, v120
	v_exp_f32_e32 v185, v121
	v_exp_f32_e32 v186, v122
	v_exp_f32_e32 v187, v123
	s_waitcnt lgkmcnt(4)
	v_mfma_f32_32x32x16_bf16 v[64:79], v[140:143], v[176:179], v[64:79]
	v_exp_f32_e32 v136, v124
	v_exp_f32_e32 v137, v125
	v_exp_f32_e32 v138, v126
	v_exp_f32_e32 v139, v127
	s_waitcnt lgkmcnt(3)
	v_mfma_f32_32x32x16_bf16 v[80:95], v[144:147], v[172:175], v[80:95]
	v_exp_f32_e32 v140, v96
	v_exp_f32_e32 v141, v97
	v_exp_f32_e32 v142, v98
	v_exp_f32_e32 v143, v99
	s_waitcnt lgkmcnt(2)
	v_mfma_f32_32x32x16_bf16 v[64:79], v[148:151], v[172:175], v[64:79]
	v_exp_f32_e32 v144, v100
	v_exp_f32_e32 v145, v101
	v_exp_f32_e32 v146, v102
	v_exp_f32_e32 v147, v103
	s_waitcnt lgkmcnt(1)
	v_mfma_f32_32x32x16_bf16 v[80:95], v[152:155], v[168:171], v[80:95]
	v_exp_f32_e32 v148, v104
	v_exp_f32_e32 v149, v105
	v_exp_f32_e32 v150, v106
	v_exp_f32_e32 v151, v107
	s_waitcnt lgkmcnt(0)
	v_mfma_f32_32x32x16_bf16 v[64:79], v[156:159], v[168:171], v[64:79]
	v_exp_f32_e32 v152, v108
	v_exp_f32_e32 v153, v109
	v_exp_f32_e32 v154, v110
	v_exp_f32_e32 v155, v111
	s_cmp_gt_i32 s27, 2
	s_cselect_b32 s34, -3, 2
	s_waitcnt vmcnt(3)
	ds_write_b128 v208, v[128:131]
	v_add_u32_e32 v128, s29, v195
	ds_read_b128 v[240:243], v195 offset:27648
	ds_read_b128 v[244:247], v195 offset:32256
	ds_read_b128 v[96:99], v128 offset:41472
	ds_read_b128 v[100:103], v128 offset:36864
	ds_read_b128 v[104:107], v128 offset:36896
	ds_read_b128 v[108:111], v128 offset:41504
	ds_read_b128 v[116:119], v128 offset:36928
	ds_read_b128 v[120:123], v128 offset:41536
	ds_read_b128 v[124:127], v128 offset:36960
	ds_read_b128 v[128:131], v128 offset:41568
	s_add_i32 s34, s34, s27
	s_add_i32 s29, s13, -2
	s_mulk_i32 s34, 0x2400
	s_min_u32 s29, s29, s12
	v_add_u32_e32 v15, s34, v208
	s_lshl_b32 s92, s29, 13
	s_waitcnt vmcnt(2)
	ds_write_b128 v15, v[10:13] offset:36864
	s_add_u32 vcc_lo, s100, s92
	s_addc_u32 vcc_hi, s101, 0
	global_load_dwordx4 v[10:13], v248, vcc
	s_lshl_b32 s92, s28, 7
	v_add_f32_e32 v1, v1, v14
	s_add_u32 vcc_lo, s98, s92
	s_addc_u32 vcc_hi, s99, 0
	global_load_dwordx4 v[112:115], v249, vcc
	s_add_i32 s34, s27, 1
	s_setprio 1
	v_cvt_pk_bf16_f32 v132, v160, v161
	v_cvt_pk_bf16_f32 v133, v162, v163
	v_cvt_pk_bf16_f32 v134, v164, v165
	v_cvt_pk_bf16_f32 v135, v166, v167
	s_waitcnt lgkmcnt(7)
	s_nop 0
	v_mfma_f32_32x32x16_bf16 v[16:31], v[100:103], v[132:135], v[16:31]
	v_add_f32_e32 v14, v160, v161
	v_add_f32_e32 v14, v14, v162
	v_add_f32_e32 v14, v14, v163
	s_nop 0
	v_mfma_f32_32x32x16_bf16 v[32:47], v[96:99], v[132:135], v[32:47]
	v_cvt_pk_bf16_f32 v100, v184, v185
	v_cvt_pk_bf16_f32 v101, v186, v187
	v_cvt_pk_bf16_f32 v102, v136, v137
	v_cvt_pk_bf16_f32 v103, v138, v139
	v_add_f32_e32 v14, v14, v164
	v_add_f32_e32 v14, v14, v165
	v_add_f32_e32 v14, v14, v166
	v_add_f32_e32 v14, v14, v167
	s_waitcnt lgkmcnt(6)
	v_mfma_f32_32x32x16_bf16 v[16:31], v[104:107], v[100:103], v[16:31]
	v_add_f32_e32 v14, v14, v184
	v_add_f32_e32 v14, v14, v185
	v_add_f32_e32 v14, v14, v186
	v_add_f32_e32 v14, v14, v187
	s_waitcnt lgkmcnt(5)
	v_mfma_f32_32x32x16_bf16 v[32:47], v[108:111], v[100:103], v[32:47]
	v_cvt_pk_bf16_f32 v96, v140, v141
	v_cvt_pk_bf16_f32 v97, v142, v143
	v_cvt_pk_bf16_f32 v98, v144, v145
	v_cvt_pk_bf16_f32 v99, v146, v147
	v_add_f32_e32 v14, v14, v136
	v_add_f32_e32 v14, v14, v137
	v_add_f32_e32 v14, v14, v138
	v_add_f32_e32 v14, v14, v139
	s_waitcnt lgkmcnt(4)
	v_mfma_f32_32x32x16_bf16 v[16:31], v[116:119], v[96:99], v[16:31]
	v_add_f32_e32 v14, v14, v140
	v_add_f32_e32 v14, v14, v141
	v_add_f32_e32 v14, v14, v142
	v_add_f32_e32 v14, v14, v143
	s_waitcnt lgkmcnt(3)
	v_mfma_f32_32x32x16_bf16 v[32:47], v[120:123], v[96:99], v[32:47]
	v_cvt_pk_bf16_f32 v100, v148, v149
	v_cvt_pk_bf16_f32 v101, v150, v151
	v_cvt_pk_bf16_f32 v102, v152, v153
	v_cvt_pk_bf16_f32 v103, v154, v155
	v_add_f32_e32 v14, v14, v144
	v_add_f32_e32 v14, v14, v145
	v_add_f32_e32 v14, v14, v146
	v_add_f32_e32 v14, v14, v147
	s_waitcnt lgkmcnt(2)
	v_mfma_f32_32x32x16_bf16 v[16:31], v[124:127], v[100:103], v[16:31]
	v_add_f32_e32 v14, v14, v148
	v_add_f32_e32 v14, v14, v149
	v_add_f32_e32 v14, v14, v150
	v_add_f32_e32 v14, v14, v151
	s_waitcnt lgkmcnt(1)
	v_mfma_f32_32x32x16_bf16 v[32:47], v[128:131], v[100:103], v[32:47]
	v_add_f32_e32 v14, v14, v152
	v_add_f32_e32 v14, v14, v153
	v_add_f32_e32 v14, v14, v154
	v_add_f32_e32 v14, v14, v155
	s_setprio 0
	ds_read_b128 v[116:119], v195 offset:27680
	ds_read_b128 v[124:127], v195 offset:32288
	ds_read_b128 v[128:131], v195 offset:27712
	ds_read_b128 v[132:135], v195 offset:27744
	ds_read_b128 v[136:139], v195 offset:32320
	ds_read_b128 v[140:143], v195 offset:32352
	s_cmp_lg_u32 s27, 4
	s_cselect_b32 s27, s34, 0
	s_waitcnt lgkmcnt(6)
	v_mfma_f32_32x32x16_bf16 v[152:167], v[240:243], v[180:183], v[48:63]
	v_exp_f32_e32 v15, v80
	v_exp_f32_e32 v144, v81
	v_exp_f32_e32 v145, v82
	v_exp_f32_e32 v146, v83
	s_waitcnt lgkmcnt(5)
	v_mfma_f32_32x32x16_bf16 v[96:111], v[244:247], v[180:183], v[48:63]
	v_exp_f32_e32 v147, v84
	v_exp_f32_e32 v148, v85
	v_exp_f32_e32 v149, v86
	v_exp_f32_e32 v150, v87
	v_mfma_f32_32x32x16_bf16 v[152:167], v[116:119], v[176:179], v[152:167]
	v_exp_f32_e32 v120, v88
	v_exp_f32_e32 v121, v89
	v_exp_f32_e32 v122, v90
	v_exp_f32_e32 v123, v91
	s_waitcnt lgkmcnt(4)
	v_mfma_f32_32x32x16_bf16 v[96:111], v[124:127], v[176:179], v[96:111]
	v_exp_f32_e32 v151, v92
	v_exp_f32_e32 v184, v93
	v_exp_f32_e32 v185, v94
	v_exp_f32_e32 v186, v95
	s_waitcnt lgkmcnt(3)
	v_mfma_f32_32x32x16_bf16 v[152:167], v[128:131], v[172:175], v[152:167]
	v_exp_f32_e32 v124, v64
	v_exp_f32_e32 v125, v65
	v_exp_f32_e32 v126, v66
	v_exp_f32_e32 v127, v67
	s_waitcnt lgkmcnt(1)
	v_mfma_f32_32x32x16_bf16 v[96:111], v[136:139], v[172:175], v[96:111]
	v_exp_f32_e32 v128, v68
	v_exp_f32_e32 v129, v69
	v_exp_f32_e32 v130, v70
	v_exp_f32_e32 v131, v71
	v_mfma_f32_32x32x16_bf16 v[152:167], v[132:135], v[168:171], v[152:167]
	v_exp_f32_e32 v136, v72
	v_exp_f32_e32 v137, v73
	v_exp_f32_e32 v138, v74
	v_exp_f32_e32 v139, v75
	s_waitcnt lgkmcnt(0)
	v_mfma_f32_32x32x16_bf16 v[96:111], v[140:143], v[168:171], v[96:111]
	v_exp_f32_e32 v132, v76
	v_exp_f32_e32 v133, v77
	v_exp_f32_e32 v134, v78
	v_exp_f32_e32 v135, v79
	s_mul_i32 vcc_lo, s27, 0x2400
	v_add_u32_e32 v251, vcc_lo, v195
	ds_read_b128 v[240:243], v251 offset:36864
	ds_read_b128 v[244:247], v251 offset:41472
	s_cmp_gt_i32 s27, 2
	s_cselect_b32 s28, -3, 2
	s_add_i32 s28, s28, s27
	s_mulk_i32 s28, 0x2400
	s_waitcnt vmcnt(3)
	ds_write_b128 v208, v[6:9] offset:9216
	v_add_u32_e32 v6, s28, v208
	s_add_i32 s28, s27, 1
	s_cmp_lg_u32 s27, 4
	s_cselect_b32 s27, s28, 0
	s_add_i32 s28, s13, -1
	s_min_u32 s28, s28, s12
	s_lshl_b32 s92, s28, 13
	s_waitcnt vmcnt(2)
	ds_write_b128 v6, v[2:5] offset:36864
	s_add_u32 vcc_lo, s100, s92
	s_addc_u32 vcc_hi, s101, 0
	global_load_dwordx4 v[6:9], v248, vcc
	s_lshl_b32 s92, s29, 7
	s_add_u32 vcc_lo, s98, s92
	s_addc_u32 vcc_hi, s99, 0
	global_load_dwordx4 v[2:5], v249, vcc
	s_nop 0
	s_mul_i32 s29, s27, 0x2400
	s_add_i32 s34, s29, 0xffffdc00
	s_cmp_lg_u32 s27, 0
	s_cselect_b32 s34, s34, 0x9000
	v_add_u32_e32 v92, s34, v195
	ds_read_b128 v[68:71], v92 offset:36896
	ds_read_b128 v[76:79], v92 offset:41504
	ds_read_b128 v[80:83], v92 offset:36928
	ds_read_b128 v[84:87], v92 offset:36960
	ds_read_b128 v[88:91], v92 offset:41536
	ds_read_b128 v[92:95], v92 offset:41568
	s_setprio 3
	v_cvt_pk_bf16_f32 v116, v15, v144
	v_cvt_pk_bf16_f32 v117, v145, v146
	v_cvt_pk_bf16_f32 v118, v147, v148
	v_cvt_pk_bf16_f32 v119, v149, v150
	s_waitcnt lgkmcnt(6)
	s_nop 0
	v_mfma_f32_32x32x16_bf16 v[16:31], v[240:243], v[116:119], v[16:31]
	v_add_f32_e32 v187, v15, v144
	v_add_f32_e32 v187, v187, v145
	v_add_f32_e32 v187, v187, v146
	v_mfma_f32_32x32x16_bf16 v[32:47], v[244:247], v[116:119], v[32:47]
	v_cvt_pk_bf16_f32 v64, v120, v121
	v_cvt_pk_bf16_f32 v65, v122, v123
	v_cvt_pk_bf16_f32 v66, v151, v184
	v_cvt_pk_bf16_f32 v67, v185, v186
	v_add_f32_e32 v187, v187, v147
	v_add_f32_e32 v187, v187, v148
	v_add_f32_e32 v187, v187, v149
	v_add_f32_e32 v187, v187, v150
	s_nop 0
	s_waitcnt lgkmcnt(5)
	v_mfma_f32_32x32x16_bf16 v[16:31], v[68:71], v[64:67], v[16:31]
	v_add_f32_e32 v187, v187, v120
	v_add_f32_e32 v187, v187, v121
	v_add_f32_e32 v187, v187, v122
	v_add_f32_e32 v187, v187, v123
	s_waitcnt lgkmcnt(4)
	v_mfma_f32_32x32x16_bf16 v[32:47], v[76:79], v[64:67], v[32:47]
	v_cvt_pk_bf16_f32 v68, v124, v125
	v_cvt_pk_bf16_f32 v69, v126, v127
	v_cvt_pk_bf16_f32 v70, v128, v129
	v_cvt_pk_bf16_f32 v71, v130, v131
	v_add_f32_e32 v187, v187, v151
	v_add_f32_e32 v187, v187, v184
	v_add_f32_e32 v187, v187, v185
	v_add_f32_e32 v187, v187, v186
	s_waitcnt lgkmcnt(3)
	v_mfma_f32_32x32x16_bf16 v[16:31], v[80:83], v[68:71], v[16:31]
	v_add_f32_e32 v187, v187, v124
	v_add_f32_e32 v187, v187, v125
	v_add_f32_e32 v187, v187, v126
	v_add_f32_e32 v187, v187, v127
	s_waitcnt lgkmcnt(1)
	v_mfma_f32_32x32x16_bf16 v[32:47], v[88:91], v[68:71], v[32:47]
	v_cvt_pk_bf16_f32 v64, v136, v137
	v_cvt_pk_bf16_f32 v65, v138, v139
	v_cvt_pk_bf16_f32 v66, v132, v133
	v_cvt_pk_bf16_f32 v67, v134, v135
	v_add_f32_e32 v187, v187, v128
	v_add_f32_e32 v187, v187, v129
	v_add_f32_e32 v187, v187, v130
	v_add_f32_e32 v187, v187, v131
	s_nop 0
	v_mfma_f32_32x32x16_bf16 v[16:31], v[84:87], v[64:67], v[16:31]
	v_add_f32_e32 v187, v187, v136
	v_add_f32_e32 v187, v187, v137
	v_add_f32_e32 v187, v187, v138
	v_add_f32_e32 v187, v187, v139
	s_waitcnt lgkmcnt(0)
	v_mfma_f32_32x32x16_bf16 v[32:47], v[92:95], v[64:67], v[32:47]
	v_add_f32_e32 v187, v187, v132
	v_add_f32_e32 v187, v187, v133
	v_add_f32_e32 v187, v187, v134
	v_add_f32_e32 v187, v187, v135
	s_setprio 2
	s_waitcnt lgkmcnt(0)
	s_barrier
	ds_read_b128 v[240:243], v195
	ds_read_b128 v[244:247], v195 offset:4608
	ds_read_b128 v[72:75], v195 offset:32
	ds_read_b128 v[76:79], v195 offset:4640
	ds_read_b128 v[80:83], v195 offset:64
	ds_read_b128 v[84:87], v195 offset:4672
	ds_read_b128 v[88:91], v195 offset:96
	ds_read_b128 v[92:95], v195 offset:4704
	v_add_f32_e32 v1, v1, v14
	v_exp_f32_e32 v14, v152
	v_exp_f32_e32 v15, v153
	v_exp_f32_e32 v116, v154
	v_exp_f32_e32 v117, v155
	s_waitcnt lgkmcnt(6)
	v_mfma_f32_32x32x16_bf16 v[136:151], v[240:243], v[180:183], v[48:63]
	v_mfma_f32_32x32x16_bf16 v[120:135], v[244:247], v[180:183], v[48:63]
	v_exp_f32_e32 v118, v156
	v_exp_f32_e32 v119, v157
	v_exp_f32_e32 v184, v158
	v_exp_f32_e32 v185, v159
	s_waitcnt lgkmcnt(5)
	v_mfma_f32_32x32x16_bf16 v[136:151], v[72:75], v[176:179], v[136:151]
	v_exp_f32_e32 v186, v160
	v_exp_f32_e32 v210, v161
	v_exp_f32_e32 v211, v162
	v_exp_f32_e32 v212, v163
	s_waitcnt lgkmcnt(4)
	v_mfma_f32_32x32x16_bf16 v[120:135], v[76:79], v[176:179], v[120:135]
	v_exp_f32_e32 v160, v164
	v_exp_f32_e32 v161, v165
	v_exp_f32_e32 v162, v166
	v_exp_f32_e32 v163, v167
	s_waitcnt lgkmcnt(3)
	v_mfma_f32_32x32x16_bf16 v[136:151], v[80:83], v[172:175], v[136:151]
	v_exp_f32_e32 v164, v96
	v_exp_f32_e32 v165, v97
	v_exp_f32_e32 v166, v98
	v_exp_f32_e32 v167, v99
	s_waitcnt lgkmcnt(2)
	v_mfma_f32_32x32x16_bf16 v[120:135], v[84:87], v[172:175], v[120:135]
	v_exp_f32_e32 v96, v100
	v_exp_f32_e32 v97, v101
	v_exp_f32_e32 v98, v102
	v_exp_f32_e32 v99, v103
	s_waitcnt lgkmcnt(1)
	v_mfma_f32_32x32x16_bf16 v[136:151], v[88:91], v[168:171], v[136:151]
	v_exp_f32_e32 v100, v104
	v_exp_f32_e32 v101, v105
	v_exp_f32_e32 v102, v106
	v_exp_f32_e32 v103, v107
	s_waitcnt lgkmcnt(0)
	v_mfma_f32_32x32x16_bf16 v[120:135], v[92:95], v[168:171], v[120:135]
	v_exp_f32_e32 v104, v108
	v_exp_f32_e32 v105, v109
	v_exp_f32_e32 v106, v110
	v_exp_f32_e32 v107, v111
	s_cmp_gt_i32 s27, 2
	s_cselect_b32 s34, -3, 2
	s_add_i32 s34, s34, s27
	s_mulk_i32 s34, 0x2400
	v_add_u32_e32 v88, s29, v195
	s_min_u32 s29, s13, s12
	s_waitcnt vmcnt(3)
	ds_write_b128 v208, v[10:13] offset:18432
	v_add_u32_e32 v10, s34, v208
	s_lshl_b32 s92, s29, 13
	s_waitcnt vmcnt(2)
	ds_write_b128 v10, v[112:115] offset:36864
	ds_read_b128 v[240:243], v195 offset:9216
	ds_read_b128 v[244:247], v195 offset:13824
	ds_read_b128 v[10:13], v88 offset:41472
	ds_read_b128 v[64:67], v88 offset:36864
	ds_read_b128 v[68:71], v88 offset:36896
	ds_read_b128 v[72:75], v88 offset:41504
	ds_read_b128 v[76:79], v88 offset:36928
	ds_read_b128 v[80:83], v88 offset:41536
	ds_read_b128 v[84:87], v88 offset:36960
	ds_read_b128 v[88:91], v88 offset:41568
	s_add_u32 vcc_lo, s100, s92
	s_addc_u32 vcc_hi, s101, 0
	global_load_dwordx4 v[152:155], v248, vcc
	s_lshl_b32 s92, s28, 7
	s_add_u32 vcc_lo, s98, s92
	s_addc_u32 vcc_hi, s99, 0
	global_load_dwordx4 v[156:159], v249, vcc
	v_add_f32_e32 v1, v1, v187
	s_setprio 1
	v_mov_b32_e32 v109, v136
	v_cvt_pk_bf16_f32 v92, v14, v15
	v_cvt_pk_bf16_f32 v93, v116, v117
	v_cvt_pk_bf16_f32 v94, v118, v119
	v_cvt_pk_bf16_f32 v95, v184, v185
	s_waitcnt lgkmcnt(6)
	s_nop 0
	v_mfma_f32_32x32x16_bf16 v[16:31], v[64:67], v[92:95], v[16:31]
	v_max3_f32 v109, v109, v137, v138
	v_max3_f32 v109, v109, v139, v140
	v_add_f32_e32 v108, v14, v15
	v_add_f32_e32 v108, v108, v116
	v_add_f32_e32 v108, v108, v117
	s_nop 0
	v_mfma_f32_32x32x16_bf16 v[32:47], v[10:13], v[92:95], v[32:47]
	v_cvt_pk_bf16_f32 v64, v186, v210
	v_cvt_pk_bf16_f32 v65, v211, v212
	v_cvt_pk_bf16_f32 v66, v160, v161
	v_cvt_pk_bf16_f32 v67, v162, v163
	v_max3_f32 v109, v109, v141, v142
	v_max3_f32 v109, v109, v143, v144
	v_add_f32_e32 v108, v108, v118
	v_add_f32_e32 v108, v108, v119
	v_add_f32_e32 v108, v108, v184
	v_add_f32_e32 v108, v108, v185
	s_waitcnt lgkmcnt(5)
	v_mfma_f32_32x32x16_bf16 v[16:31], v[68:71], v[64:67], v[16:31]
	v_max3_f32 v109, v109, v145, v146
	v_max3_f32 v109, v109, v147, v148
	v_add_f32_e32 v108, v108, v186
	v_add_f32_e32 v108, v108, v210
	v_add_f32_e32 v108, v108, v211
	v_add_f32_e32 v108, v108, v212
	s_waitcnt lgkmcnt(4)
	v_mfma_f32_32x32x16_bf16 v[32:47], v[72:75], v[64:67], v[32:47]
	v_cvt_pk_bf16_f32 v10, v164, v165
	v_cvt_pk_bf16_f32 v11, v166, v167
	v_cvt_pk_bf16_f32 v12, v96, v97
	v_cvt_pk_bf16_f32 v13, v98, v99
	v_max3_f32 v109, v109, v149, v150
	v_max3_f32 v109, v109, v151, v120
	v_add_f32_e32 v108, v108, v160
	v_add_f32_e32 v108, v108, v161
	v_add_f32_e32 v108, v108, v162
	v_add_f32_e32 v108, v108, v163
	s_waitcnt lgkmcnt(3)
	v_mfma_f32_32x32x16_bf16 v[16:31], v[76:79], v[10:13], v[16:31]
	v_max3_f32 v109, v109, v121, v122
	v_max3_f32 v109, v109, v123, v124
	v_add_f32_e32 v108, v108, v164
	v_add_f32_e32 v108, v108, v165
	v_add_f32_e32 v108, v108, v166
	v_add_f32_e32 v108, v108, v167
	s_waitcnt lgkmcnt(2)
	v_mfma_f32_32x32x16_bf16 v[32:47], v[80:83], v[10:13], v[32:47]
	v_cvt_pk_bf16_f32 v64, v100, v101
	v_cvt_pk_bf16_f32 v65, v102, v103
	v_cvt_pk_bf16_f32 v66, v104, v105
	v_cvt_pk_bf16_f32 v67, v106, v107
	v_max3_f32 v109, v109, v125, v126
	v_max3_f32 v109, v109, v127, v128
	v_add_f32_e32 v108, v108, v96
	v_add_f32_e32 v108, v108, v97
	v_add_f32_e32 v108, v108, v98
	v_add_f32_e32 v108, v108, v99
	s_waitcnt lgkmcnt(1)
	v_mfma_f32_32x32x16_bf16 v[16:31], v[84:87], v[64:67], v[16:31]
	v_max3_f32 v109, v109, v129, v130
	v_max3_f32 v109, v109, v131, v132
	v_add_f32_e32 v108, v108, v100
	v_add_f32_e32 v108, v108, v101
	v_add_f32_e32 v108, v108, v102
	v_add_f32_e32 v108, v108, v103
	s_waitcnt lgkmcnt(0)
	v_mfma_f32_32x32x16_bf16 v[32:47], v[88:91], v[64:67], v[32:47]
	v_max3_f32 v109, v109, v133, v134
	v_max3_f32 v109, v109, v135, v135
	v_add_f32_e32 v108, v108, v104
	v_add_f32_e32 v108, v108, v105
	v_add_f32_e32 v108, v108, v106
	v_add_f32_e32 v108, v108, v107
	s_setprio 0
	ds_read_b128 v[164:167], v195 offset:9248
	ds_read_b128 v[160:163], v195 offset:13856
	ds_read_b128 v[74:77], v195 offset:9280
	ds_read_b128 v[66:69], v195 offset:9312
	ds_read_b128 v[70:73], v195 offset:13888
	ds_read_b128 v[10:13], v195 offset:13920
	v_add_f32_e32 v64, v1, v108
	v_mov_b32_e32 v1, v109
	s_nop 1
	v_permlane32_swap_b32_e32 v109, v1
	v_max_f32_e32 v1, v1, v1
	v_max_f32_e32 v14, v109, v109
	v_max_f32_e32 v1, v14, v1
	v_cmp_lt_f32_e32 vcc, s52, v1
	s_cbranch_vccz .LBB0_663
	v_max_f32_e32 v1, v1, v1
	v_max_f32_e32 v14, 0, v1
	v_add_f32_e32 v209, v209, v14
	v_xor_b32_e32 v48, 0x80000000, v209
	v_pk_add_f32 v[136:137], v[136:137], v[14:15] op_sel_hi:[1,0] neg_lo:[0,1] neg_hi:[0,1]
	v_pk_add_f32 v[120:121], v[120:121], v[14:15] op_sel_hi:[1,0] neg_lo:[0,1] neg_hi:[0,1]
	v_pk_add_f32 v[138:139], v[138:139], v[14:15] op_sel_hi:[1,0] neg_lo:[0,1] neg_hi:[0,1]
	v_pk_add_f32 v[122:123], v[122:123], v[14:15] op_sel_hi:[1,0] neg_lo:[0,1] neg_hi:[0,1]
	v_pk_add_f32 v[140:141], v[140:141], v[14:15] op_sel_hi:[1,0] neg_lo:[0,1] neg_hi:[0,1]
	v_pk_add_f32 v[124:125], v[124:125], v[14:15] op_sel_hi:[1,0] neg_lo:[0,1] neg_hi:[0,1]
	v_pk_add_f32 v[142:143], v[142:143], v[14:15] op_sel_hi:[1,0] neg_lo:[0,1] neg_hi:[0,1]
	v_pk_add_f32 v[126:127], v[126:127], v[14:15] op_sel_hi:[1,0] neg_lo:[0,1] neg_hi:[0,1]
	v_pk_add_f32 v[144:145], v[144:145], v[14:15] op_sel_hi:[1,0] neg_lo:[0,1] neg_hi:[0,1]
	v_pk_add_f32 v[128:129], v[128:129], v[14:15] op_sel_hi:[1,0] neg_lo:[0,1] neg_hi:[0,1]
	v_pk_add_f32 v[146:147], v[146:147], v[14:15] op_sel_hi:[1,0] neg_lo:[0,1] neg_hi:[0,1]
	v_pk_add_f32 v[130:131], v[130:131], v[14:15] op_sel_hi:[1,0] neg_lo:[0,1] neg_hi:[0,1]
	v_pk_add_f32 v[148:149], v[148:149], v[14:15] op_sel_hi:[1,0] neg_lo:[0,1] neg_hi:[0,1]
	v_pk_add_f32 v[132:133], v[132:133], v[14:15] op_sel_hi:[1,0] neg_lo:[0,1] neg_hi:[0,1]
	v_pk_add_f32 v[150:151], v[150:151], v[14:15] op_sel_hi:[1,0] neg_lo:[0,1] neg_hi:[0,1]
	v_pk_add_f32 v[134:135], v[134:135], v[14:15] op_sel_hi:[1,0] neg_lo:[0,1] neg_hi:[0,1]
	v_exp_f32_e64 v14, -v14
	v_mov_b32_e32 v49, v48
	v_mov_b32_e32 v50, v48
	v_mov_b32_e32 v51, v48
	v_mov_b32_e32 v52, v48
	v_mov_b32_e32 v53, v48
	v_mov_b32_e32 v54, v48
	v_mov_b32_e32 v55, v48
	v_mov_b32_e32 v56, v48
	v_mov_b32_e32 v57, v48
	v_mov_b32_e32 v58, v48
	v_mov_b32_e32 v59, v48
	v_mov_b32_e32 v60, v48
	v_mov_b32_e32 v61, v48
	v_mov_b32_e32 v62, v48
	v_mov_b32_e32 v63, v48
	s_nop 11
	v_pk_mul_f32 v[30:31], v[30:31], v[14:15] op_sel_hi:[1,0]
	v_pk_mul_f32 v[28:29], v[28:29], v[14:15] op_sel_hi:[1,0]
	v_pk_mul_f32 v[26:27], v[26:27], v[14:15] op_sel_hi:[1,0]
	v_pk_mul_f32 v[24:25], v[24:25], v[14:15] op_sel_hi:[1,0]
	v_pk_mul_f32 v[22:23], v[22:23], v[14:15] op_sel_hi:[1,0]
	v_pk_mul_f32 v[20:21], v[20:21], v[14:15] op_sel_hi:[1,0]
	v_pk_mul_f32 v[18:19], v[18:19], v[14:15] op_sel_hi:[1,0]
	v_pk_mul_f32 v[16:17], v[16:17], v[14:15] op_sel_hi:[1,0]
	v_pk_mul_f32 v[46:47], v[46:47], v[14:15] op_sel_hi:[1,0]
	v_pk_mul_f32 v[44:45], v[44:45], v[14:15] op_sel_hi:[1,0]
	v_pk_mul_f32 v[42:43], v[42:43], v[14:15] op_sel_hi:[1,0]
	v_pk_mul_f32 v[40:41], v[40:41], v[14:15] op_sel_hi:[1,0]
	v_pk_mul_f32 v[38:39], v[38:39], v[14:15] op_sel_hi:[1,0]
	v_pk_mul_f32 v[36:37], v[36:37], v[14:15] op_sel_hi:[1,0]
	v_pk_mul_f32 v[34:35], v[34:35], v[14:15] op_sel_hi:[1,0]
	v_pk_mul_f32 v[32:33], v[32:33], v[14:15] op_sel_hi:[1,0]
	v_mul_f32_e32 v64, v64, v14
